# P9 fused epilogue: the f32 U stores are issued after the partial statistics are published so that they overlap the wait for the sibling workgroups
# speedup vs baseline: 1.0912x; 1.0092x over previous
.LBB0_1460:
	v_lshlrev_b32_e32 v130, 3, v153
	v_and_b32_e32 v190, 0x78, v130
	v_ashrrev_i32_e32 v152, 4, v153
	v_lshrrev_b32_e32 v130, 1, v153
	v_and_b32_e32 v191, 0x60, v130
	v_or_b32_e32 v130, 4, v190
	v_lshlrev_b32_e32 v132, 2, v152
	v_bitop3_b32 v133, v132, v190, 48 bitop3:0x6c
	v_bitop3_b32 v132, v132, v130, 48 bitop3:0x6c
	v_lshlrev_b32_e32 v134, 9, v152
	v_lshlrev_b32_e32 v132, 2, v132
	v_add_u32_e32 v151, 32, v152
	v_lshlrev_b32_e32 v133, 2, v133
	v_add3_u32 v148, s64, v132, v134
	v_lshlrev_b32_e32 v132, 2, v151
	v_add3_u32 v147, s64, v133, v134
	v_bitop3_b32 v133, v132, v190, 48 bitop3:0x6c
	v_bitop3_b32 v132, v132, v130, 48 bitop3:0x6c
	v_lshlrev_b32_e32 v134, 9, v151
	v_lshlrev_b32_e32 v132, 2, v132
	v_add_u32_e32 v150, 64, v152
	v_lshlrev_b32_e32 v133, 2, v133
	v_add3_u32 v145, s64, v132, v134
	v_lshlrev_b32_e32 v132, 2, v150
	v_add3_u32 v146, s64, v133, v134
	v_bitop3_b32 v133, v132, v190, 48 bitop3:0x6c
	v_bitop3_b32 v132, v132, v130, 48 bitop3:0x6c
	v_lshlrev_b32_e32 v134, 9, v150
	v_lshlrev_b32_e32 v132, 2, v132
	v_add_u32_e32 v149, 0x60, v152
	v_lshlrev_b32_e32 v133, 2, v133
	v_add3_u32 v143, s64, v132, v134
	v_lshlrev_b32_e32 v132, 2, v149
	v_add3_u32 v144, s64, v133, v134
	v_bitop3_b32 v133, v132, v190, 48 bitop3:0x6c
	v_bitop3_b32 v130, v132, v130, 48 bitop3:0x6c
	v_lshlrev_b32_e32 v133, 2, v133
	v_lshlrev_b32_e32 v134, 9, v149
	v_lshlrev_b32_e32 v130, 2, v130
	s_lshl_b64 s[50:51], s[46:47], 2
	v_add3_u32 v141, s64, v133, v134
	v_add3_u32 v140, s64, v130, v134
	v_bfe_u32 v189, v153, 4, 2
	v_and_b32_e32 v188, 15, v153
	v_lshlrev_b32_e32 v193, 4, v189
	v_lshlrev_b32_e32 v153, 7, v153
	v_or_b32_e32 v192, v191, v188
	v_bitop3_b32 v188, v191, v193, v188 bitop3:0x36
	v_and_b32_e32 v153, 0xffff8000, v153
	v_lshlrev_b32_e32 v188, 2, v188
	v_lshl_or_b32 v189, v189, 11, v153
	v_add3_u32 v153, s64, v188, v189
	v_bitop3_b32 v149, v192, v193, 16 bitop3:0x36
	v_lshlrev_b32_e32 v149, 2, v149
	v_add3_u32 v149, s64, v149, v189
	v_lshrrev_b32_e32 v227, 4, v0
	v_add_u32_e32 v130, s73, v227
	v_lshlrev_b32_e32 v227, 3, v227
	v_and_b32_e32 v226, 15, v0
	v_lshlrev_b32_e32 v226, 5, v226
	s_lshl_b32 s0, s46, 2
	v_add_u32_e32 v226, s0, v226
	v_mov_b32_e32 v229, 0
	v_mov_b32_e32 v228, v130
	v_lshlrev_b64 v[228:229], 12, v[228:229]
	v_mov_b32_e32 v230, v226
	v_mov_b32_e32 v231, 0
	v_lshl_add_u64 v[228:229], v[228:229], 0, v[230:231]
	v_lshl_add_u64 v[230:231], s[66:67], 0, v[228:229]
	s_lshl_b32 s0, s73, 3
	s_add_u32 s52, s62, 0xf000000
	s_addc_u32 s53, s63, 0
	s_add_u32 s52, s52, s0
	s_addc_u32 s53, s53, 0
	v_readlane_b32 s70, v253, 8
	v_readlane_b32 s71, v253, 9
	v_readlane_b32 s74, v253, 10
	v_readlane_b32 s75, v253, 11
	s_mov_b32 s36, 0x20000
	s_mov_b32 s37, 0
	s_mov_b32 s39, 0
	s_nop 1
	s_mov_b32 s38, 0x0
	v_lshl_add_u64 v[150:151], v[230:231], 0, s[38:39]
	v_lshl_add_u64 v[220:221], v[150:151], 0, s[36:37]
	v_lshl_add_u64 v[222:223], v[220:221], 0, s[36:37]
	v_lshl_add_u64 v[224:225], v[222:223], 0, s[36:37]
	global_load_dwordx2 v[246:247], v227, s[52:53] offset:0
	global_load_dwordx2 v[248:249], v227, s[52:53] offset:256
	global_load_dwordx2 v[250:251], v227, s[52:53] offset:512
	global_load_dwordx2 v[218:219], v227, s[52:53] offset:768
	global_load_dwordx4 v[132:135], v226, s[70:71] offset:0
	global_load_dwordx4 v[136:139], v226, s[70:71] offset:16
	global_load_dwordx4 v[238:241], v226, s[74:75] offset:0
	global_load_dwordx4 v[242:245], v226, s[74:75] offset:16
	global_load_dwordx4 v[186:189], v[150:151], off
	global_load_dwordx4 v[190:193], v[150:151], off offset:16
	global_load_dwordx4 v[194:197], v[220:221], off
	global_load_dwordx4 v[198:201], v[220:221], off offset:16
	global_load_dwordx4 v[202:205], v[222:223], off
	global_load_dwordx4 v[206:209], v[222:223], off offset:16
	global_load_dwordx4 v[210:213], v[224:225], off
	global_load_dwordx4 v[214:217], v[224:225], off offset:16
	ds_write2st64_b32 v153, v126, v127 offset1:2
	ds_write2st64_b32 v153, v128, v129 offset0:4 offset1:6
	ds_write2st64_b32 v149, v98, v99 offset1:2
	ds_write2st64_b32 v149, v100, v101 offset0:4 offset1:6
	ds_write2st64_b32 v153, v102, v103 offset0:32 offset1:34
	ds_write2st64_b32 v153, v104, v105 offset0:36 offset1:38
	ds_write2st64_b32 v149, v106, v107 offset0:32 offset1:34
	ds_write2st64_b32 v149, v108, v109 offset0:36 offset1:38
	ds_write2st64_b32 v153, v110, v111 offset0:64 offset1:66
	ds_write2st64_b32 v153, v112, v113 offset0:68 offset1:70
	ds_write2st64_b32 v149, v114, v115 offset0:64 offset1:66
	ds_write2st64_b32 v149, v116, v117 offset0:68 offset1:70
	ds_write2st64_b32 v153, v118, v119 offset0:96 offset1:98
	ds_write2st64_b32 v153, v120, v121 offset0:100 offset1:102
	ds_write2st64_b32 v149, v122, v123 offset0:96 offset1:98
	ds_write2st64_b32 v149, v124, v125 offset0:100 offset1:102
	s_waitcnt lgkmcnt(0)
	s_barrier
	ds_read_b128 v[154:157], v147
	ds_read_b128 v[158:161], v148
	ds_read_b128 v[162:165], v146
	ds_read_b128 v[166:169], v145
	ds_read_b128 v[170:173], v144
	ds_read_b128 v[174:177], v143
	ds_read_b128 v[178:181], v141
	ds_read_b128 v[182:185], v140
	s_waitcnt vmcnt(0) lgkmcnt(0)
	s_barrier
	v_pk_add_f32 v[186:187], v[186:187], v[246:247] op_sel_hi:[1,0] neg_lo:[0,1] neg_hi:[0,1]
	v_pk_mul_f32 v[186:187], v[186:187], v[246:247] op_sel:[0,1]
	v_pk_fma_f32 v[186:187], v[132:133], v[186:187], v[238:239]
	v_pk_fma_f32 v[98:99], v[186:187], s[42:43], v[154:155] op_sel_hi:[1,0,1]
	v_pk_add_f32 v[188:189], v[188:189], v[246:247] op_sel_hi:[1,0] neg_lo:[0,1] neg_hi:[0,1]
	v_pk_mul_f32 v[188:189], v[188:189], v[246:247] op_sel:[0,1]
	v_pk_fma_f32 v[188:189], v[134:135], v[188:189], v[240:241]
	v_pk_fma_f32 v[100:101], v[188:189], s[42:43], v[156:157] op_sel_hi:[1,0,1]
	v_pk_add_f32 v[190:191], v[190:191], v[246:247] op_sel_hi:[1,0] neg_lo:[0,1] neg_hi:[0,1]
	v_pk_mul_f32 v[190:191], v[190:191], v[246:247] op_sel:[0,1]
	v_pk_fma_f32 v[190:191], v[136:137], v[190:191], v[242:243]
	v_pk_fma_f32 v[102:103], v[190:191], s[42:43], v[158:159] op_sel_hi:[1,0,1]
	v_pk_add_f32 v[192:193], v[192:193], v[246:247] op_sel_hi:[1,0] neg_lo:[0,1] neg_hi:[0,1]
	v_pk_mul_f32 v[192:193], v[192:193], v[246:247] op_sel:[0,1]
	v_pk_fma_f32 v[192:193], v[138:139], v[192:193], v[244:245]
	v_pk_fma_f32 v[104:105], v[192:193], s[42:43], v[160:161] op_sel_hi:[1,0,1]
	v_pk_add_f32 v[194:195], v[194:195], v[248:249] op_sel_hi:[1,0] neg_lo:[0,1] neg_hi:[0,1]
	v_pk_mul_f32 v[194:195], v[194:195], v[248:249] op_sel:[0,1]
	v_pk_fma_f32 v[194:195], v[132:133], v[194:195], v[238:239]
	v_pk_fma_f32 v[106:107], v[194:195], s[42:43], v[162:163] op_sel_hi:[1,0,1]
	v_pk_add_f32 v[196:197], v[196:197], v[248:249] op_sel_hi:[1,0] neg_lo:[0,1] neg_hi:[0,1]
	v_pk_mul_f32 v[196:197], v[196:197], v[248:249] op_sel:[0,1]
	v_pk_fma_f32 v[196:197], v[134:135], v[196:197], v[240:241]
	v_pk_fma_f32 v[108:109], v[196:197], s[42:43], v[164:165] op_sel_hi:[1,0,1]
	v_pk_add_f32 v[198:199], v[198:199], v[248:249] op_sel_hi:[1,0] neg_lo:[0,1] neg_hi:[0,1]
	v_pk_mul_f32 v[198:199], v[198:199], v[248:249] op_sel:[0,1]
	v_pk_fma_f32 v[198:199], v[136:137], v[198:199], v[242:243]
	v_pk_fma_f32 v[110:111], v[198:199], s[42:43], v[166:167] op_sel_hi:[1,0,1]
	v_pk_add_f32 v[200:201], v[200:201], v[248:249] op_sel_hi:[1,0] neg_lo:[0,1] neg_hi:[0,1]
	v_pk_mul_f32 v[200:201], v[200:201], v[248:249] op_sel:[0,1]
	v_pk_fma_f32 v[200:201], v[138:139], v[200:201], v[244:245]
	v_pk_fma_f32 v[112:113], v[200:201], s[42:43], v[168:169] op_sel_hi:[1,0,1]
	v_pk_add_f32 v[202:203], v[202:203], v[250:251] op_sel_hi:[1,0] neg_lo:[0,1] neg_hi:[0,1]
	v_pk_mul_f32 v[202:203], v[202:203], v[250:251] op_sel:[0,1]
	v_pk_fma_f32 v[202:203], v[132:133], v[202:203], v[238:239]
	v_pk_fma_f32 v[114:115], v[202:203], s[42:43], v[170:171] op_sel_hi:[1,0,1]
	v_pk_add_f32 v[204:205], v[204:205], v[250:251] op_sel_hi:[1,0] neg_lo:[0,1] neg_hi:[0,1]
	v_pk_mul_f32 v[204:205], v[204:205], v[250:251] op_sel:[0,1]
	v_pk_fma_f32 v[204:205], v[134:135], v[204:205], v[240:241]
	v_pk_fma_f32 v[116:117], v[204:205], s[42:43], v[172:173] op_sel_hi:[1,0,1]
	v_pk_add_f32 v[206:207], v[206:207], v[250:251] op_sel_hi:[1,0] neg_lo:[0,1] neg_hi:[0,1]
	v_pk_mul_f32 v[206:207], v[206:207], v[250:251] op_sel:[0,1]
	v_pk_fma_f32 v[206:207], v[136:137], v[206:207], v[242:243]
	v_pk_fma_f32 v[118:119], v[206:207], s[42:43], v[174:175] op_sel_hi:[1,0,1]
	v_pk_add_f32 v[208:209], v[208:209], v[250:251] op_sel_hi:[1,0] neg_lo:[0,1] neg_hi:[0,1]
	v_pk_mul_f32 v[208:209], v[208:209], v[250:251] op_sel:[0,1]
	v_pk_fma_f32 v[208:209], v[138:139], v[208:209], v[244:245]
	v_pk_fma_f32 v[120:121], v[208:209], s[42:43], v[176:177] op_sel_hi:[1,0,1]
	v_pk_add_f32 v[210:211], v[210:211], v[218:219] op_sel_hi:[1,0] neg_lo:[0,1] neg_hi:[0,1]
	v_pk_mul_f32 v[210:211], v[210:211], v[218:219] op_sel:[0,1]
	v_pk_fma_f32 v[210:211], v[132:133], v[210:211], v[238:239]
	v_pk_fma_f32 v[122:123], v[210:211], s[42:43], v[178:179] op_sel_hi:[1,0,1]
	v_pk_add_f32 v[212:213], v[212:213], v[218:219] op_sel_hi:[1,0] neg_lo:[0,1] neg_hi:[0,1]
	v_pk_mul_f32 v[212:213], v[212:213], v[218:219] op_sel:[0,1]
	v_pk_fma_f32 v[212:213], v[134:135], v[212:213], v[240:241]
	v_pk_fma_f32 v[124:125], v[212:213], s[42:43], v[180:181] op_sel_hi:[1,0,1]
	v_pk_add_f32 v[214:215], v[214:215], v[218:219] op_sel_hi:[1,0] neg_lo:[0,1] neg_hi:[0,1]
	v_pk_mul_f32 v[214:215], v[214:215], v[218:219] op_sel:[0,1]
	v_pk_fma_f32 v[214:215], v[136:137], v[214:215], v[242:243]
	v_pk_fma_f32 v[126:127], v[214:215], s[42:43], v[182:183] op_sel_hi:[1,0,1]
	v_pk_add_f32 v[216:217], v[216:217], v[218:219] op_sel_hi:[1,0] neg_lo:[0,1] neg_hi:[0,1]
	v_pk_mul_f32 v[216:217], v[216:217], v[218:219] op_sel:[0,1]
	v_pk_fma_f32 v[216:217], v[138:139], v[216:217], v[244:245]
	v_pk_fma_f32 v[128:129], v[216:217], s[42:43], v[184:185] op_sel_hi:[1,0,1]
	s_mov_b32 s38, 0x200
	v_lshl_add_u64 v[150:151], v[230:231], 0, s[38:39]
	v_lshl_add_u64 v[220:221], v[150:151], 0, s[36:37]
	v_lshl_add_u64 v[222:223], v[220:221], 0, s[36:37]
	v_lshl_add_u64 v[224:225], v[222:223], 0, s[36:37]
	global_load_dwordx2 v[246:247], v227, s[52:53] offset:0
	global_load_dwordx2 v[248:249], v227, s[52:53] offset:256
	global_load_dwordx2 v[250:251], v227, s[52:53] offset:512
	global_load_dwordx2 v[218:219], v227, s[52:53] offset:768
	global_load_dwordx4 v[132:135], v226, s[70:71] offset:512
	global_load_dwordx4 v[136:139], v226, s[70:71] offset:528
	global_load_dwordx4 v[238:241], v226, s[74:75] offset:512
	global_load_dwordx4 v[242:245], v226, s[74:75] offset:528
	global_load_dwordx4 v[186:189], v[150:151], off
	global_load_dwordx4 v[190:193], v[150:151], off offset:16
	global_load_dwordx4 v[194:197], v[220:221], off
	global_load_dwordx4 v[198:201], v[220:221], off offset:16
	global_load_dwordx4 v[202:205], v[222:223], off
	global_load_dwordx4 v[206:209], v[222:223], off offset:16
	global_load_dwordx4 v[210:213], v[224:225], off
	global_load_dwordx4 v[214:217], v[224:225], off offset:16
	ds_write2st64_b32 v153, v66, v67 offset1:2
	ds_write2st64_b32 v153, v68, v69 offset0:4 offset1:6
	ds_write2st64_b32 v149, v70, v71 offset1:2
	ds_write2st64_b32 v149, v72, v73 offset0:4 offset1:6
	ds_write2st64_b32 v153, v74, v75 offset0:32 offset1:34
	ds_write2st64_b32 v153, v76, v77 offset0:36 offset1:38
	ds_write2st64_b32 v149, v78, v79 offset0:32 offset1:34
	ds_write2st64_b32 v149, v80, v81 offset0:36 offset1:38
	ds_write2st64_b32 v153, v82, v83 offset0:64 offset1:66
	ds_write2st64_b32 v153, v84, v85 offset0:68 offset1:70
	ds_write2st64_b32 v149, v86, v87 offset0:64 offset1:66
	ds_write2st64_b32 v149, v88, v89 offset0:68 offset1:70
	ds_write2st64_b32 v153, v90, v91 offset0:96 offset1:98
	ds_write2st64_b32 v153, v92, v93 offset0:100 offset1:102
	ds_write2st64_b32 v149, v94, v95 offset0:96 offset1:98
	ds_write2st64_b32 v149, v96, v97 offset0:100 offset1:102
	s_waitcnt lgkmcnt(0)
	s_barrier
	ds_read_b128 v[154:157], v147
	ds_read_b128 v[158:161], v148
	ds_read_b128 v[162:165], v146
	ds_read_b128 v[166:169], v145
	ds_read_b128 v[170:173], v144
	ds_read_b128 v[174:177], v143
	ds_read_b128 v[178:181], v141
	ds_read_b128 v[182:185], v140
	s_waitcnt vmcnt(0) lgkmcnt(0)
	s_barrier
	v_pk_add_f32 v[186:187], v[186:187], v[246:247] op_sel_hi:[1,0] neg_lo:[0,1] neg_hi:[0,1]
	v_pk_mul_f32 v[186:187], v[186:187], v[246:247] op_sel:[0,1]
	v_pk_fma_f32 v[186:187], v[132:133], v[186:187], v[238:239]
	v_pk_fma_f32 v[66:67], v[186:187], s[42:43], v[154:155] op_sel_hi:[1,0,1]
	v_pk_add_f32 v[188:189], v[188:189], v[246:247] op_sel_hi:[1,0] neg_lo:[0,1] neg_hi:[0,1]
	v_pk_mul_f32 v[188:189], v[188:189], v[246:247] op_sel:[0,1]
	v_pk_fma_f32 v[188:189], v[134:135], v[188:189], v[240:241]
	v_pk_fma_f32 v[68:69], v[188:189], s[42:43], v[156:157] op_sel_hi:[1,0,1]
	v_pk_add_f32 v[190:191], v[190:191], v[246:247] op_sel_hi:[1,0] neg_lo:[0,1] neg_hi:[0,1]
	v_pk_mul_f32 v[190:191], v[190:191], v[246:247] op_sel:[0,1]
	v_pk_fma_f32 v[190:191], v[136:137], v[190:191], v[242:243]
	v_pk_fma_f32 v[70:71], v[190:191], s[42:43], v[158:159] op_sel_hi:[1,0,1]
	v_pk_add_f32 v[192:193], v[192:193], v[246:247] op_sel_hi:[1,0] neg_lo:[0,1] neg_hi:[0,1]
	v_pk_mul_f32 v[192:193], v[192:193], v[246:247] op_sel:[0,1]
	v_pk_fma_f32 v[192:193], v[138:139], v[192:193], v[244:245]
	v_pk_fma_f32 v[72:73], v[192:193], s[42:43], v[160:161] op_sel_hi:[1,0,1]
	v_pk_add_f32 v[194:195], v[194:195], v[248:249] op_sel_hi:[1,0] neg_lo:[0,1] neg_hi:[0,1]
	v_pk_mul_f32 v[194:195], v[194:195], v[248:249] op_sel:[0,1]
	v_pk_fma_f32 v[194:195], v[132:133], v[194:195], v[238:239]
	v_pk_fma_f32 v[74:75], v[194:195], s[42:43], v[162:163] op_sel_hi:[1,0,1]
	v_pk_add_f32 v[196:197], v[196:197], v[248:249] op_sel_hi:[1,0] neg_lo:[0,1] neg_hi:[0,1]
	v_pk_mul_f32 v[196:197], v[196:197], v[248:249] op_sel:[0,1]
	v_pk_fma_f32 v[196:197], v[134:135], v[196:197], v[240:241]
	v_pk_fma_f32 v[76:77], v[196:197], s[42:43], v[164:165] op_sel_hi:[1,0,1]
	v_pk_add_f32 v[198:199], v[198:199], v[248:249] op_sel_hi:[1,0] neg_lo:[0,1] neg_hi:[0,1]
	v_pk_mul_f32 v[198:199], v[198:199], v[248:249] op_sel:[0,1]
	v_pk_fma_f32 v[198:199], v[136:137], v[198:199], v[242:243]
	v_pk_fma_f32 v[78:79], v[198:199], s[42:43], v[166:167] op_sel_hi:[1,0,1]
	v_pk_add_f32 v[200:201], v[200:201], v[248:249] op_sel_hi:[1,0] neg_lo:[0,1] neg_hi:[0,1]
	v_pk_mul_f32 v[200:201], v[200:201], v[248:249] op_sel:[0,1]
	v_pk_fma_f32 v[200:201], v[138:139], v[200:201], v[244:245]
	v_pk_fma_f32 v[80:81], v[200:201], s[42:43], v[168:169] op_sel_hi:[1,0,1]
	v_pk_add_f32 v[202:203], v[202:203], v[250:251] op_sel_hi:[1,0] neg_lo:[0,1] neg_hi:[0,1]
	v_pk_mul_f32 v[202:203], v[202:203], v[250:251] op_sel:[0,1]
	v_pk_fma_f32 v[202:203], v[132:133], v[202:203], v[238:239]
	v_pk_fma_f32 v[82:83], v[202:203], s[42:43], v[170:171] op_sel_hi:[1,0,1]
	v_pk_add_f32 v[204:205], v[204:205], v[250:251] op_sel_hi:[1,0] neg_lo:[0,1] neg_hi:[0,1]
	v_pk_mul_f32 v[204:205], v[204:205], v[250:251] op_sel:[0,1]
	v_pk_fma_f32 v[204:205], v[134:135], v[204:205], v[240:241]
	v_pk_fma_f32 v[84:85], v[204:205], s[42:43], v[172:173] op_sel_hi:[1,0,1]
	v_pk_add_f32 v[206:207], v[206:207], v[250:251] op_sel_hi:[1,0] neg_lo:[0,1] neg_hi:[0,1]
	v_pk_mul_f32 v[206:207], v[206:207], v[250:251] op_sel:[0,1]
	v_pk_fma_f32 v[206:207], v[136:137], v[206:207], v[242:243]
	v_pk_fma_f32 v[86:87], v[206:207], s[42:43], v[174:175] op_sel_hi:[1,0,1]
	v_pk_add_f32 v[208:209], v[208:209], v[250:251] op_sel_hi:[1,0] neg_lo:[0,1] neg_hi:[0,1]
	v_pk_mul_f32 v[208:209], v[208:209], v[250:251] op_sel:[0,1]
	v_pk_fma_f32 v[208:209], v[138:139], v[208:209], v[244:245]
	v_pk_fma_f32 v[88:89], v[208:209], s[42:43], v[176:177] op_sel_hi:[1,0,1]
	v_pk_add_f32 v[210:211], v[210:211], v[218:219] op_sel_hi:[1,0] neg_lo:[0,1] neg_hi:[0,1]
	v_pk_mul_f32 v[210:211], v[210:211], v[218:219] op_sel:[0,1]
	v_pk_fma_f32 v[210:211], v[132:133], v[210:211], v[238:239]
	v_pk_fma_f32 v[90:91], v[210:211], s[42:43], v[178:179] op_sel_hi:[1,0,1]
	v_pk_add_f32 v[212:213], v[212:213], v[218:219] op_sel_hi:[1,0] neg_lo:[0,1] neg_hi:[0,1]
	v_pk_mul_f32 v[212:213], v[212:213], v[218:219] op_sel:[0,1]
	v_pk_fma_f32 v[212:213], v[134:135], v[212:213], v[240:241]
	v_pk_fma_f32 v[92:93], v[212:213], s[42:43], v[180:181] op_sel_hi:[1,0,1]
	v_pk_add_f32 v[214:215], v[214:215], v[218:219] op_sel_hi:[1,0] neg_lo:[0,1] neg_hi:[0,1]
	v_pk_mul_f32 v[214:215], v[214:215], v[218:219] op_sel:[0,1]
	v_pk_fma_f32 v[214:215], v[136:137], v[214:215], v[242:243]
	v_pk_fma_f32 v[94:95], v[214:215], s[42:43], v[182:183] op_sel_hi:[1,0,1]
	v_pk_add_f32 v[216:217], v[216:217], v[218:219] op_sel_hi:[1,0] neg_lo:[0,1] neg_hi:[0,1]
	v_pk_mul_f32 v[216:217], v[216:217], v[218:219] op_sel:[0,1]
	v_pk_fma_f32 v[216:217], v[138:139], v[216:217], v[244:245]
	v_pk_fma_f32 v[96:97], v[216:217], s[42:43], v[184:185] op_sel_hi:[1,0,1]
	s_mov_b32 s38, 0x80000
	v_lshl_add_u64 v[150:151], v[230:231], 0, s[38:39]
	v_lshl_add_u64 v[220:221], v[150:151], 0, s[36:37]
	v_lshl_add_u64 v[222:223], v[220:221], 0, s[36:37]
	v_lshl_add_u64 v[224:225], v[222:223], 0, s[36:37]
	global_load_dwordx2 v[246:247], v227, s[52:53] offset:1024
	global_load_dwordx2 v[248:249], v227, s[52:53] offset:1280
	global_load_dwordx2 v[250:251], v227, s[52:53] offset:1536
	global_load_dwordx2 v[218:219], v227, s[52:53] offset:1792
	global_load_dwordx4 v[132:135], v226, s[70:71] offset:0
	global_load_dwordx4 v[136:139], v226, s[70:71] offset:16
	global_load_dwordx4 v[238:241], v226, s[74:75] offset:0
	global_load_dwordx4 v[242:245], v226, s[74:75] offset:16
	global_load_dwordx4 v[186:189], v[150:151], off
	global_load_dwordx4 v[190:193], v[150:151], off offset:16
	global_load_dwordx4 v[194:197], v[220:221], off
	global_load_dwordx4 v[198:201], v[220:221], off offset:16
	global_load_dwordx4 v[202:205], v[222:223], off
	global_load_dwordx4 v[206:209], v[222:223], off offset:16
	global_load_dwordx4 v[210:213], v[224:225], off
	global_load_dwordx4 v[214:217], v[224:225], off offset:16
	ds_write2st64_b32 v153, v34, v35 offset1:2
	ds_write2st64_b32 v153, v36, v37 offset0:4 offset1:6
	ds_write2st64_b32 v149, v38, v39 offset1:2
	ds_write2st64_b32 v149, v40, v41 offset0:4 offset1:6
	ds_write2st64_b32 v153, v42, v43 offset0:32 offset1:34
	ds_write2st64_b32 v153, v44, v45 offset0:36 offset1:38
	ds_write2st64_b32 v149, v46, v47 offset0:32 offset1:34
	ds_write2st64_b32 v149, v48, v49 offset0:36 offset1:38
	ds_write2st64_b32 v153, v50, v51 offset0:64 offset1:66
	ds_write2st64_b32 v153, v52, v53 offset0:68 offset1:70
	ds_write2st64_b32 v149, v54, v55 offset0:64 offset1:66
	ds_write2st64_b32 v149, v56, v57 offset0:68 offset1:70
	ds_write2st64_b32 v153, v58, v59 offset0:96 offset1:98
	ds_write2st64_b32 v153, v60, v61 offset0:100 offset1:102
	ds_write2st64_b32 v149, v62, v63 offset0:96 offset1:98
	ds_write2st64_b32 v149, v64, v65 offset0:100 offset1:102
	s_waitcnt lgkmcnt(0)
	s_barrier
	ds_read_b128 v[154:157], v147
	ds_read_b128 v[158:161], v148
	ds_read_b128 v[162:165], v146
	ds_read_b128 v[166:169], v145
	ds_read_b128 v[170:173], v144
	ds_read_b128 v[174:177], v143
	ds_read_b128 v[178:181], v141
	ds_read_b128 v[182:185], v140
	s_waitcnt vmcnt(0) lgkmcnt(0)
	s_barrier
	v_pk_add_f32 v[186:187], v[186:187], v[246:247] op_sel_hi:[1,0] neg_lo:[0,1] neg_hi:[0,1]
	v_pk_mul_f32 v[186:187], v[186:187], v[246:247] op_sel:[0,1]
	v_pk_fma_f32 v[186:187], v[132:133], v[186:187], v[238:239]
	v_pk_fma_f32 v[34:35], v[186:187], s[42:43], v[154:155] op_sel_hi:[1,0,1]
	v_pk_add_f32 v[188:189], v[188:189], v[246:247] op_sel_hi:[1,0] neg_lo:[0,1] neg_hi:[0,1]
	v_pk_mul_f32 v[188:189], v[188:189], v[246:247] op_sel:[0,1]
	v_pk_fma_f32 v[188:189], v[134:135], v[188:189], v[240:241]
	v_pk_fma_f32 v[36:37], v[188:189], s[42:43], v[156:157] op_sel_hi:[1,0,1]
	v_pk_add_f32 v[190:191], v[190:191], v[246:247] op_sel_hi:[1,0] neg_lo:[0,1] neg_hi:[0,1]
	v_pk_mul_f32 v[190:191], v[190:191], v[246:247] op_sel:[0,1]
	v_pk_fma_f32 v[190:191], v[136:137], v[190:191], v[242:243]
	v_pk_fma_f32 v[38:39], v[190:191], s[42:43], v[158:159] op_sel_hi:[1,0,1]
	v_pk_add_f32 v[192:193], v[192:193], v[246:247] op_sel_hi:[1,0] neg_lo:[0,1] neg_hi:[0,1]
	v_pk_mul_f32 v[192:193], v[192:193], v[246:247] op_sel:[0,1]
	v_pk_fma_f32 v[192:193], v[138:139], v[192:193], v[244:245]
	v_pk_fma_f32 v[40:41], v[192:193], s[42:43], v[160:161] op_sel_hi:[1,0,1]
	v_pk_add_f32 v[194:195], v[194:195], v[248:249] op_sel_hi:[1,0] neg_lo:[0,1] neg_hi:[0,1]
	v_pk_mul_f32 v[194:195], v[194:195], v[248:249] op_sel:[0,1]
	v_pk_fma_f32 v[194:195], v[132:133], v[194:195], v[238:239]
	v_pk_fma_f32 v[42:43], v[194:195], s[42:43], v[162:163] op_sel_hi:[1,0,1]
	v_pk_add_f32 v[196:197], v[196:197], v[248:249] op_sel_hi:[1,0] neg_lo:[0,1] neg_hi:[0,1]
	v_pk_mul_f32 v[196:197], v[196:197], v[248:249] op_sel:[0,1]
	v_pk_fma_f32 v[196:197], v[134:135], v[196:197], v[240:241]
	v_pk_fma_f32 v[44:45], v[196:197], s[42:43], v[164:165] op_sel_hi:[1,0,1]
	v_pk_add_f32 v[198:199], v[198:199], v[248:249] op_sel_hi:[1,0] neg_lo:[0,1] neg_hi:[0,1]
	v_pk_mul_f32 v[198:199], v[198:199], v[248:249] op_sel:[0,1]
	v_pk_fma_f32 v[198:199], v[136:137], v[198:199], v[242:243]
	v_pk_fma_f32 v[46:47], v[198:199], s[42:43], v[166:167] op_sel_hi:[1,0,1]
	v_pk_add_f32 v[200:201], v[200:201], v[248:249] op_sel_hi:[1,0] neg_lo:[0,1] neg_hi:[0,1]
	v_pk_mul_f32 v[200:201], v[200:201], v[248:249] op_sel:[0,1]
	v_pk_fma_f32 v[200:201], v[138:139], v[200:201], v[244:245]
	v_pk_fma_f32 v[48:49], v[200:201], s[42:43], v[168:169] op_sel_hi:[1,0,1]
	v_pk_add_f32 v[202:203], v[202:203], v[250:251] op_sel_hi:[1,0] neg_lo:[0,1] neg_hi:[0,1]
	v_pk_mul_f32 v[202:203], v[202:203], v[250:251] op_sel:[0,1]
	v_pk_fma_f32 v[202:203], v[132:133], v[202:203], v[238:239]
	v_pk_fma_f32 v[50:51], v[202:203], s[42:43], v[170:171] op_sel_hi:[1,0,1]
	v_pk_add_f32 v[204:205], v[204:205], v[250:251] op_sel_hi:[1,0] neg_lo:[0,1] neg_hi:[0,1]
	v_pk_mul_f32 v[204:205], v[204:205], v[250:251] op_sel:[0,1]
	v_pk_fma_f32 v[204:205], v[134:135], v[204:205], v[240:241]
	v_pk_fma_f32 v[52:53], v[204:205], s[42:43], v[172:173] op_sel_hi:[1,0,1]
	v_pk_add_f32 v[206:207], v[206:207], v[250:251] op_sel_hi:[1,0] neg_lo:[0,1] neg_hi:[0,1]
	v_pk_mul_f32 v[206:207], v[206:207], v[250:251] op_sel:[0,1]
	v_pk_fma_f32 v[206:207], v[136:137], v[206:207], v[242:243]
	v_pk_fma_f32 v[54:55], v[206:207], s[42:43], v[174:175] op_sel_hi:[1,0,1]
	v_pk_add_f32 v[208:209], v[208:209], v[250:251] op_sel_hi:[1,0] neg_lo:[0,1] neg_hi:[0,1]
	v_pk_mul_f32 v[208:209], v[208:209], v[250:251] op_sel:[0,1]
	v_pk_fma_f32 v[208:209], v[138:139], v[208:209], v[244:245]
	v_pk_fma_f32 v[56:57], v[208:209], s[42:43], v[176:177] op_sel_hi:[1,0,1]
	v_pk_add_f32 v[210:211], v[210:211], v[218:219] op_sel_hi:[1,0] neg_lo:[0,1] neg_hi:[0,1]
	v_pk_mul_f32 v[210:211], v[210:211], v[218:219] op_sel:[0,1]
	v_pk_fma_f32 v[210:211], v[132:133], v[210:211], v[238:239]
	v_pk_fma_f32 v[58:59], v[210:211], s[42:43], v[178:179] op_sel_hi:[1,0,1]
	v_pk_add_f32 v[212:213], v[212:213], v[218:219] op_sel_hi:[1,0] neg_lo:[0,1] neg_hi:[0,1]
	v_pk_mul_f32 v[212:213], v[212:213], v[218:219] op_sel:[0,1]
	v_pk_fma_f32 v[212:213], v[134:135], v[212:213], v[240:241]
	v_pk_fma_f32 v[60:61], v[212:213], s[42:43], v[180:181] op_sel_hi:[1,0,1]
	v_pk_add_f32 v[214:215], v[214:215], v[218:219] op_sel_hi:[1,0] neg_lo:[0,1] neg_hi:[0,1]
	v_pk_mul_f32 v[214:215], v[214:215], v[218:219] op_sel:[0,1]
	v_pk_fma_f32 v[214:215], v[136:137], v[214:215], v[242:243]
	v_pk_fma_f32 v[62:63], v[214:215], s[42:43], v[182:183] op_sel_hi:[1,0,1]
	v_pk_add_f32 v[216:217], v[216:217], v[218:219] op_sel_hi:[1,0] neg_lo:[0,1] neg_hi:[0,1]
	v_pk_mul_f32 v[216:217], v[216:217], v[218:219] op_sel:[0,1]
	v_pk_fma_f32 v[216:217], v[138:139], v[216:217], v[244:245]
	v_pk_fma_f32 v[64:65], v[216:217], s[42:43], v[184:185] op_sel_hi:[1,0,1]
	s_mov_b32 s38, 0x80200
	v_lshl_add_u64 v[150:151], v[230:231], 0, s[38:39]
	v_lshl_add_u64 v[220:221], v[150:151], 0, s[36:37]
	v_lshl_add_u64 v[222:223], v[220:221], 0, s[36:37]
	v_lshl_add_u64 v[224:225], v[222:223], 0, s[36:37]
	global_load_dwordx2 v[246:247], v227, s[52:53] offset:1024
	global_load_dwordx2 v[248:249], v227, s[52:53] offset:1280
	global_load_dwordx2 v[250:251], v227, s[52:53] offset:1536
	global_load_dwordx2 v[218:219], v227, s[52:53] offset:1792
	global_load_dwordx4 v[132:135], v226, s[70:71] offset:512
	global_load_dwordx4 v[136:139], v226, s[70:71] offset:528
	global_load_dwordx4 v[238:241], v226, s[74:75] offset:512
	global_load_dwordx4 v[242:245], v226, s[74:75] offset:528
	global_load_dwordx4 v[186:189], v[150:151], off
	global_load_dwordx4 v[190:193], v[150:151], off offset:16
	global_load_dwordx4 v[194:197], v[220:221], off
	global_load_dwordx4 v[198:201], v[220:221], off offset:16
	global_load_dwordx4 v[202:205], v[222:223], off
	global_load_dwordx4 v[206:209], v[222:223], off offset:16
	global_load_dwordx4 v[210:213], v[224:225], off
	global_load_dwordx4 v[214:217], v[224:225], off offset:16
	ds_write2st64_b32 v153, v2, v3 offset1:2
	ds_write2st64_b32 v153, v4, v5 offset0:4 offset1:6
	ds_write2st64_b32 v149, v6, v7 offset1:2
	ds_write2st64_b32 v149, v8, v9 offset0:4 offset1:6
	ds_write2st64_b32 v153, v10, v11 offset0:32 offset1:34
	ds_write2st64_b32 v153, v12, v13 offset0:36 offset1:38
	ds_write2st64_b32 v149, v14, v15 offset0:32 offset1:34
	ds_write2st64_b32 v149, v16, v17 offset0:36 offset1:38
	ds_write2st64_b32 v153, v18, v19 offset0:64 offset1:66
	ds_write2st64_b32 v153, v20, v21 offset0:68 offset1:70
	ds_write2st64_b32 v149, v22, v23 offset0:64 offset1:66
	ds_write2st64_b32 v149, v24, v25 offset0:68 offset1:70
	ds_write2st64_b32 v153, v26, v27 offset0:96 offset1:98
	ds_write2st64_b32 v153, v28, v29 offset0:100 offset1:102
	ds_write2st64_b32 v149, v30, v31 offset0:96 offset1:98
	ds_write2st64_b32 v149, v32, v33 offset0:100 offset1:102
	s_waitcnt lgkmcnt(0)
	s_barrier
	ds_read_b128 v[154:157], v147
	ds_read_b128 v[158:161], v148
	ds_read_b128 v[162:165], v146
	ds_read_b128 v[166:169], v145
	ds_read_b128 v[170:173], v144
	ds_read_b128 v[174:177], v143
	ds_read_b128 v[178:181], v141
	ds_read_b128 v[182:185], v140
	s_waitcnt vmcnt(0) lgkmcnt(0)
	v_pk_add_f32 v[186:187], v[186:187], v[246:247] op_sel_hi:[1,0] neg_lo:[0,1] neg_hi:[0,1]
	v_pk_mul_f32 v[186:187], v[186:187], v[246:247] op_sel:[0,1]
	v_pk_fma_f32 v[186:187], v[132:133], v[186:187], v[238:239]
	v_pk_fma_f32 v[2:3], v[186:187], s[42:43], v[154:155] op_sel_hi:[1,0,1]
	v_pk_add_f32 v[188:189], v[188:189], v[246:247] op_sel_hi:[1,0] neg_lo:[0,1] neg_hi:[0,1]
	v_pk_mul_f32 v[188:189], v[188:189], v[246:247] op_sel:[0,1]
	v_pk_fma_f32 v[188:189], v[134:135], v[188:189], v[240:241]
	v_pk_fma_f32 v[4:5], v[188:189], s[42:43], v[156:157] op_sel_hi:[1,0,1]
	v_pk_add_f32 v[190:191], v[190:191], v[246:247] op_sel_hi:[1,0] neg_lo:[0,1] neg_hi:[0,1]
	v_pk_mul_f32 v[190:191], v[190:191], v[246:247] op_sel:[0,1]
	v_pk_fma_f32 v[190:191], v[136:137], v[190:191], v[242:243]
	v_pk_fma_f32 v[6:7], v[190:191], s[42:43], v[158:159] op_sel_hi:[1,0,1]
	v_pk_add_f32 v[192:193], v[192:193], v[246:247] op_sel_hi:[1,0] neg_lo:[0,1] neg_hi:[0,1]
	v_pk_mul_f32 v[192:193], v[192:193], v[246:247] op_sel:[0,1]
	v_pk_fma_f32 v[192:193], v[138:139], v[192:193], v[244:245]
	v_pk_fma_f32 v[8:9], v[192:193], s[42:43], v[160:161] op_sel_hi:[1,0,1]
	v_pk_add_f32 v[194:195], v[194:195], v[248:249] op_sel_hi:[1,0] neg_lo:[0,1] neg_hi:[0,1]
	v_pk_mul_f32 v[194:195], v[194:195], v[248:249] op_sel:[0,1]
	v_pk_fma_f32 v[194:195], v[132:133], v[194:195], v[238:239]
	v_pk_fma_f32 v[10:11], v[194:195], s[42:43], v[162:163] op_sel_hi:[1,0,1]
	v_pk_add_f32 v[196:197], v[196:197], v[248:249] op_sel_hi:[1,0] neg_lo:[0,1] neg_hi:[0,1]
	v_pk_mul_f32 v[196:197], v[196:197], v[248:249] op_sel:[0,1]
	v_pk_fma_f32 v[196:197], v[134:135], v[196:197], v[240:241]
	v_pk_fma_f32 v[12:13], v[196:197], s[42:43], v[164:165] op_sel_hi:[1,0,1]
	v_pk_add_f32 v[198:199], v[198:199], v[248:249] op_sel_hi:[1,0] neg_lo:[0,1] neg_hi:[0,1]
	v_pk_mul_f32 v[198:199], v[198:199], v[248:249] op_sel:[0,1]
	v_pk_fma_f32 v[198:199], v[136:137], v[198:199], v[242:243]
	v_pk_fma_f32 v[14:15], v[198:199], s[42:43], v[166:167] op_sel_hi:[1,0,1]
	v_pk_add_f32 v[200:201], v[200:201], v[248:249] op_sel_hi:[1,0] neg_lo:[0,1] neg_hi:[0,1]
	v_pk_mul_f32 v[200:201], v[200:201], v[248:249] op_sel:[0,1]
	v_pk_fma_f32 v[200:201], v[138:139], v[200:201], v[244:245]
	v_pk_fma_f32 v[16:17], v[200:201], s[42:43], v[168:169] op_sel_hi:[1,0,1]
	v_pk_add_f32 v[202:203], v[202:203], v[250:251] op_sel_hi:[1,0] neg_lo:[0,1] neg_hi:[0,1]
	v_pk_mul_f32 v[202:203], v[202:203], v[250:251] op_sel:[0,1]
	v_pk_fma_f32 v[202:203], v[132:133], v[202:203], v[238:239]
	v_pk_fma_f32 v[18:19], v[202:203], s[42:43], v[170:171] op_sel_hi:[1,0,1]
	v_pk_add_f32 v[204:205], v[204:205], v[250:251] op_sel_hi:[1,0] neg_lo:[0,1] neg_hi:[0,1]
	v_pk_mul_f32 v[204:205], v[204:205], v[250:251] op_sel:[0,1]
	v_pk_fma_f32 v[204:205], v[134:135], v[204:205], v[240:241]
	v_pk_fma_f32 v[20:21], v[204:205], s[42:43], v[172:173] op_sel_hi:[1,0,1]
	v_pk_add_f32 v[206:207], v[206:207], v[250:251] op_sel_hi:[1,0] neg_lo:[0,1] neg_hi:[0,1]
	v_pk_mul_f32 v[206:207], v[206:207], v[250:251] op_sel:[0,1]
	v_pk_fma_f32 v[206:207], v[136:137], v[206:207], v[242:243]
	v_pk_fma_f32 v[22:23], v[206:207], s[42:43], v[174:175] op_sel_hi:[1,0,1]
	v_pk_add_f32 v[208:209], v[208:209], v[250:251] op_sel_hi:[1,0] neg_lo:[0,1] neg_hi:[0,1]
	v_pk_mul_f32 v[208:209], v[208:209], v[250:251] op_sel:[0,1]
	v_pk_fma_f32 v[208:209], v[138:139], v[208:209], v[244:245]
	v_pk_fma_f32 v[24:25], v[208:209], s[42:43], v[176:177] op_sel_hi:[1,0,1]
	v_pk_add_f32 v[210:211], v[210:211], v[218:219] op_sel_hi:[1,0] neg_lo:[0,1] neg_hi:[0,1]
	v_pk_mul_f32 v[210:211], v[210:211], v[218:219] op_sel:[0,1]
	v_pk_fma_f32 v[210:211], v[132:133], v[210:211], v[238:239]
	v_pk_fma_f32 v[26:27], v[210:211], s[42:43], v[178:179] op_sel_hi:[1,0,1]
	v_pk_add_f32 v[212:213], v[212:213], v[218:219] op_sel_hi:[1,0] neg_lo:[0,1] neg_hi:[0,1]
	v_pk_mul_f32 v[212:213], v[212:213], v[218:219] op_sel:[0,1]
	v_pk_fma_f32 v[212:213], v[134:135], v[212:213], v[240:241]
	v_pk_fma_f32 v[28:29], v[212:213], s[42:43], v[180:181] op_sel_hi:[1,0,1]
	v_pk_add_f32 v[214:215], v[214:215], v[218:219] op_sel_hi:[1,0] neg_lo:[0,1] neg_hi:[0,1]
	v_pk_mul_f32 v[214:215], v[214:215], v[218:219] op_sel:[0,1]
	v_pk_fma_f32 v[214:215], v[136:137], v[214:215], v[242:243]
	v_pk_fma_f32 v[30:31], v[214:215], s[42:43], v[182:183] op_sel_hi:[1,0,1]
	v_pk_add_f32 v[216:217], v[216:217], v[218:219] op_sel_hi:[1,0] neg_lo:[0,1] neg_hi:[0,1]
	v_pk_mul_f32 v[216:217], v[216:217], v[218:219] op_sel:[0,1]
	v_pk_fma_f32 v[216:217], v[138:139], v[216:217], v[244:245]
	v_pk_fma_f32 v[32:33], v[216:217], s[42:43], v[184:185] op_sel_hi:[1,0,1]
	v_readlane_b32 s70, v253, 18
	v_readlane_b32 s71, v253, 19
	v_readlane_b32 s74, v253, 20
	v_readlane_b32 s75, v253, 21
	v_lshrrev_b64 v[222:223], 1, v[228:229]
	v_lshl_add_u64 v[222:223], s[60:61], 0, v[222:223]
	s_nop 2
	global_load_dwordx4 v[186:189], v226, s[70:71] offset:0
	global_load_dwordx4 v[190:193], v226, s[70:71] offset:16
	global_load_dwordx4 v[194:197], v226, s[70:71] offset:512
	global_load_dwordx4 v[198:201], v226, s[70:71] offset:528
	global_load_dwordx4 v[202:205], v226, s[74:75] offset:0
	global_load_dwordx4 v[206:209], v226, s[74:75] offset:16
	global_load_dwordx4 v[210:213], v226, s[74:75] offset:512
	global_load_dwordx4 v[214:217], v226, s[74:75] offset:528
	v_pk_add_f32 v[154:155], v[98:99], v[100:101]
	v_pk_add_f32 v[156:157], v[106:107], v[108:109]
	v_pk_add_f32 v[158:159], v[114:115], v[116:117]
	v_pk_add_f32 v[160:161], v[122:123], v[124:125]
	v_pk_add_f32 v[162:163], v[34:35], v[36:37]
	v_pk_add_f32 v[164:165], v[42:43], v[44:45]
	v_pk_add_f32 v[166:167], v[50:51], v[52:53]
	v_pk_add_f32 v[168:169], v[58:59], v[60:61]
	v_pk_add_f32 v[154:155], v[154:155], v[102:103]
	v_pk_add_f32 v[156:157], v[156:157], v[110:111]
	v_pk_add_f32 v[158:159], v[158:159], v[118:119]
	v_pk_add_f32 v[160:161], v[160:161], v[126:127]
	v_pk_add_f32 v[162:163], v[162:163], v[38:39]
	v_pk_add_f32 v[164:165], v[164:165], v[46:47]
	v_pk_add_f32 v[166:167], v[166:167], v[54:55]
	v_pk_add_f32 v[168:169], v[168:169], v[62:63]
	v_pk_add_f32 v[154:155], v[154:155], v[104:105]
	v_pk_add_f32 v[156:157], v[156:157], v[112:113]
	v_pk_add_f32 v[158:159], v[158:159], v[120:121]
	v_pk_add_f32 v[160:161], v[160:161], v[128:129]
	v_pk_add_f32 v[162:163], v[162:163], v[40:41]
	v_pk_add_f32 v[164:165], v[164:165], v[48:49]
	v_pk_add_f32 v[166:167], v[166:167], v[56:57]
	v_pk_add_f32 v[168:169], v[168:169], v[64:65]
	v_pk_add_f32 v[154:155], v[154:155], v[66:67]
	v_pk_add_f32 v[156:157], v[156:157], v[74:75]
	v_pk_add_f32 v[158:159], v[158:159], v[82:83]
	v_pk_add_f32 v[160:161], v[160:161], v[90:91]
	v_pk_add_f32 v[162:163], v[162:163], v[2:3]
	v_pk_add_f32 v[164:165], v[164:165], v[10:11]
	v_pk_add_f32 v[166:167], v[166:167], v[18:19]
	v_pk_add_f32 v[168:169], v[168:169], v[26:27]
	v_pk_add_f32 v[154:155], v[154:155], v[68:69]
	v_pk_add_f32 v[156:157], v[156:157], v[76:77]
	v_pk_add_f32 v[158:159], v[158:159], v[84:85]
	v_pk_add_f32 v[160:161], v[160:161], v[92:93]
	v_pk_add_f32 v[162:163], v[162:163], v[4:5]
	v_pk_add_f32 v[164:165], v[164:165], v[12:13]
	v_pk_add_f32 v[166:167], v[166:167], v[20:21]
	v_pk_add_f32 v[168:169], v[168:169], v[28:29]
	v_pk_add_f32 v[154:155], v[154:155], v[70:71]
	v_pk_add_f32 v[156:157], v[156:157], v[78:79]
	v_pk_add_f32 v[158:159], v[158:159], v[86:87]
	v_pk_add_f32 v[160:161], v[160:161], v[94:95]
	v_pk_add_f32 v[162:163], v[162:163], v[6:7]
	v_pk_add_f32 v[164:165], v[164:165], v[14:15]
	v_pk_add_f32 v[166:167], v[166:167], v[22:23]
	v_pk_add_f32 v[168:169], v[168:169], v[30:31]
	v_pk_add_f32 v[154:155], v[154:155], v[72:73]
	v_pk_add_f32 v[156:157], v[156:157], v[80:81]
	v_pk_add_f32 v[158:159], v[158:159], v[88:89]
	v_pk_add_f32 v[160:161], v[160:161], v[96:97]
	v_pk_add_f32 v[162:163], v[162:163], v[8:9]
	v_pk_add_f32 v[164:165], v[164:165], v[16:17]
	v_pk_add_f32 v[166:167], v[166:167], v[24:25]
	v_pk_add_f32 v[168:169], v[168:169], v[32:33]
	v_add_f32_e32 v132, v154, v155
	v_add_f32_e32 v134, v156, v157
	v_add_f32_e32 v136, v158, v159
	v_add_f32_e32 v138, v160, v161
	v_add_f32_e32 v232, v162, v163
	v_add_f32_e32 v234, v164, v165
	v_add_f32_e32 v236, v166, v167
	v_add_f32_e32 v150, v168, v169
	v_add_f32_dpp v132, v132, v132 quad_perm:[1,0,3,2] row_mask:0xf bank_mask:0xf
	v_add_f32_dpp v134, v134, v134 quad_perm:[1,0,3,2] row_mask:0xf bank_mask:0xf
	v_add_f32_dpp v136, v136, v136 quad_perm:[1,0,3,2] row_mask:0xf bank_mask:0xf
	v_add_f32_dpp v138, v138, v138 quad_perm:[1,0,3,2] row_mask:0xf bank_mask:0xf
	v_add_f32_dpp v232, v232, v232 quad_perm:[1,0,3,2] row_mask:0xf bank_mask:0xf
	v_add_f32_dpp v234, v234, v234 quad_perm:[1,0,3,2] row_mask:0xf bank_mask:0xf
	v_add_f32_dpp v236, v236, v236 quad_perm:[1,0,3,2] row_mask:0xf bank_mask:0xf
	v_add_f32_dpp v150, v150, v150 quad_perm:[1,0,3,2] row_mask:0xf bank_mask:0xf
	v_add_f32_dpp v132, v132, v132 quad_perm:[2,3,0,1] row_mask:0xf bank_mask:0xf
	v_add_f32_dpp v134, v134, v134 quad_perm:[2,3,0,1] row_mask:0xf bank_mask:0xf
	v_add_f32_dpp v136, v136, v136 quad_perm:[2,3,0,1] row_mask:0xf bank_mask:0xf
	v_add_f32_dpp v138, v138, v138 quad_perm:[2,3,0,1] row_mask:0xf bank_mask:0xf
	v_add_f32_dpp v232, v232, v232 quad_perm:[2,3,0,1] row_mask:0xf bank_mask:0xf
	v_add_f32_dpp v234, v234, v234 quad_perm:[2,3,0,1] row_mask:0xf bank_mask:0xf
	v_add_f32_dpp v236, v236, v236 quad_perm:[2,3,0,1] row_mask:0xf bank_mask:0xf
	v_add_f32_dpp v150, v150, v150 quad_perm:[2,3,0,1] row_mask:0xf bank_mask:0xf
	v_add_f32_dpp v132, v132, v132 row_half_mirror row_mask:0xf bank_mask:0xf
	v_add_f32_dpp v134, v134, v134 row_half_mirror row_mask:0xf bank_mask:0xf
	v_add_f32_dpp v136, v136, v136 row_half_mirror row_mask:0xf bank_mask:0xf
	v_add_f32_dpp v138, v138, v138 row_half_mirror row_mask:0xf bank_mask:0xf
	v_add_f32_dpp v232, v232, v232 row_half_mirror row_mask:0xf bank_mask:0xf
	v_add_f32_dpp v234, v234, v234 row_half_mirror row_mask:0xf bank_mask:0xf
	v_add_f32_dpp v236, v236, v236 row_half_mirror row_mask:0xf bank_mask:0xf
	v_add_f32_dpp v150, v150, v150 row_half_mirror row_mask:0xf bank_mask:0xf
	v_add_f32_dpp v132, v132, v132 row_mirror row_mask:0xf bank_mask:0xf
	v_add_f32_dpp v134, v134, v134 row_mirror row_mask:0xf bank_mask:0xf
	v_add_f32_dpp v136, v136, v136 row_mirror row_mask:0xf bank_mask:0xf
	v_add_f32_dpp v138, v138, v138 row_mirror row_mask:0xf bank_mask:0xf
	v_add_f32_dpp v232, v232, v232 row_mirror row_mask:0xf bank_mask:0xf
	v_add_f32_dpp v234, v234, v234 row_mirror row_mask:0xf bank_mask:0xf
	v_add_f32_dpp v236, v236, v236 row_mirror row_mask:0xf bank_mask:0xf
	v_add_f32_dpp v150, v150, v150 row_mirror row_mask:0xf bank_mask:0xf
	v_mul_f32_e32 v132, 0x3b800000, v132
	v_mul_f32_e32 v134, 0x3b800000, v134
	v_mul_f32_e32 v136, 0x3b800000, v136
	v_mul_f32_e32 v138, 0x3b800000, v138
	v_mul_f32_e32 v232, 0x3b800000, v232
	v_mul_f32_e32 v234, 0x3b800000, v234
	v_mul_f32_e32 v236, 0x3b800000, v236
	v_mul_f32_e32 v150, 0x3b800000, v150
	v_pk_add_f32 v[218:219], v[98:99], v[132:133] op_sel_hi:[1,0] neg_lo:[0,1] neg_hi:[0,1]
	v_pk_mul_f32 v[170:171], v[218:219], v[218:219]
	v_pk_add_f32 v[220:221], v[106:107], v[134:135] op_sel_hi:[1,0] neg_lo:[0,1] neg_hi:[0,1]
	v_pk_mul_f32 v[172:173], v[220:221], v[220:221]
	v_pk_add_f32 v[218:219], v[114:115], v[136:137] op_sel_hi:[1,0] neg_lo:[0,1] neg_hi:[0,1]
	v_pk_mul_f32 v[174:175], v[218:219], v[218:219]
	v_pk_add_f32 v[220:221], v[122:123], v[138:139] op_sel_hi:[1,0] neg_lo:[0,1] neg_hi:[0,1]
	v_pk_mul_f32 v[176:177], v[220:221], v[220:221]
	v_pk_add_f32 v[218:219], v[34:35], v[232:233] op_sel_hi:[1,0] neg_lo:[0,1] neg_hi:[0,1]
	v_pk_mul_f32 v[178:179], v[218:219], v[218:219]
	v_pk_add_f32 v[220:221], v[42:43], v[234:235] op_sel_hi:[1,0] neg_lo:[0,1] neg_hi:[0,1]
	v_pk_mul_f32 v[180:181], v[220:221], v[220:221]
	v_pk_add_f32 v[218:219], v[50:51], v[236:237] op_sel_hi:[1,0] neg_lo:[0,1] neg_hi:[0,1]
	v_pk_mul_f32 v[182:183], v[218:219], v[218:219]
	v_pk_add_f32 v[220:221], v[58:59], v[150:151] op_sel_hi:[1,0] neg_lo:[0,1] neg_hi:[0,1]
	v_pk_mul_f32 v[184:185], v[220:221], v[220:221]
	v_pk_add_f32 v[218:219], v[100:101], v[132:133] op_sel_hi:[1,0] neg_lo:[0,1] neg_hi:[0,1]
	v_pk_fma_f32 v[170:171], v[218:219], v[218:219], v[170:171]
	v_pk_add_f32 v[220:221], v[108:109], v[134:135] op_sel_hi:[1,0] neg_lo:[0,1] neg_hi:[0,1]
	v_pk_fma_f32 v[172:173], v[220:221], v[220:221], v[172:173]
	v_pk_add_f32 v[218:219], v[116:117], v[136:137] op_sel_hi:[1,0] neg_lo:[0,1] neg_hi:[0,1]
	v_pk_fma_f32 v[174:175], v[218:219], v[218:219], v[174:175]
	v_pk_add_f32 v[220:221], v[124:125], v[138:139] op_sel_hi:[1,0] neg_lo:[0,1] neg_hi:[0,1]
	v_pk_fma_f32 v[176:177], v[220:221], v[220:221], v[176:177]
	v_pk_add_f32 v[218:219], v[36:37], v[232:233] op_sel_hi:[1,0] neg_lo:[0,1] neg_hi:[0,1]
	v_pk_fma_f32 v[178:179], v[218:219], v[218:219], v[178:179]
	v_pk_add_f32 v[220:221], v[44:45], v[234:235] op_sel_hi:[1,0] neg_lo:[0,1] neg_hi:[0,1]
	v_pk_fma_f32 v[180:181], v[220:221], v[220:221], v[180:181]
	v_pk_add_f32 v[218:219], v[52:53], v[236:237] op_sel_hi:[1,0] neg_lo:[0,1] neg_hi:[0,1]
	v_pk_fma_f32 v[182:183], v[218:219], v[218:219], v[182:183]
	v_pk_add_f32 v[220:221], v[60:61], v[150:151] op_sel_hi:[1,0] neg_lo:[0,1] neg_hi:[0,1]
	v_pk_fma_f32 v[184:185], v[220:221], v[220:221], v[184:185]
	v_pk_add_f32 v[218:219], v[102:103], v[132:133] op_sel_hi:[1,0] neg_lo:[0,1] neg_hi:[0,1]
	v_pk_fma_f32 v[170:171], v[218:219], v[218:219], v[170:171]
	v_pk_add_f32 v[220:221], v[110:111], v[134:135] op_sel_hi:[1,0] neg_lo:[0,1] neg_hi:[0,1]
	v_pk_fma_f32 v[172:173], v[220:221], v[220:221], v[172:173]
	v_pk_add_f32 v[218:219], v[118:119], v[136:137] op_sel_hi:[1,0] neg_lo:[0,1] neg_hi:[0,1]
	v_pk_fma_f32 v[174:175], v[218:219], v[218:219], v[174:175]
	v_pk_add_f32 v[220:221], v[126:127], v[138:139] op_sel_hi:[1,0] neg_lo:[0,1] neg_hi:[0,1]
	v_pk_fma_f32 v[176:177], v[220:221], v[220:221], v[176:177]
	v_pk_add_f32 v[218:219], v[38:39], v[232:233] op_sel_hi:[1,0] neg_lo:[0,1] neg_hi:[0,1]
	v_pk_fma_f32 v[178:179], v[218:219], v[218:219], v[178:179]
	v_pk_add_f32 v[220:221], v[46:47], v[234:235] op_sel_hi:[1,0] neg_lo:[0,1] neg_hi:[0,1]
	v_pk_fma_f32 v[180:181], v[220:221], v[220:221], v[180:181]
	v_pk_add_f32 v[218:219], v[54:55], v[236:237] op_sel_hi:[1,0] neg_lo:[0,1] neg_hi:[0,1]
	v_pk_fma_f32 v[182:183], v[218:219], v[218:219], v[182:183]
	v_pk_add_f32 v[220:221], v[62:63], v[150:151] op_sel_hi:[1,0] neg_lo:[0,1] neg_hi:[0,1]
	v_pk_fma_f32 v[184:185], v[220:221], v[220:221], v[184:185]
	v_pk_add_f32 v[218:219], v[104:105], v[132:133] op_sel_hi:[1,0] neg_lo:[0,1] neg_hi:[0,1]
	v_pk_fma_f32 v[170:171], v[218:219], v[218:219], v[170:171]
	v_pk_add_f32 v[220:221], v[112:113], v[134:135] op_sel_hi:[1,0] neg_lo:[0,1] neg_hi:[0,1]
	v_pk_fma_f32 v[172:173], v[220:221], v[220:221], v[172:173]
	v_pk_add_f32 v[218:219], v[120:121], v[136:137] op_sel_hi:[1,0] neg_lo:[0,1] neg_hi:[0,1]
	v_pk_fma_f32 v[174:175], v[218:219], v[218:219], v[174:175]
	v_pk_add_f32 v[220:221], v[128:129], v[138:139] op_sel_hi:[1,0] neg_lo:[0,1] neg_hi:[0,1]
	v_pk_fma_f32 v[176:177], v[220:221], v[220:221], v[176:177]
	v_pk_add_f32 v[218:219], v[40:41], v[232:233] op_sel_hi:[1,0] neg_lo:[0,1] neg_hi:[0,1]
	v_pk_fma_f32 v[178:179], v[218:219], v[218:219], v[178:179]
	v_pk_add_f32 v[220:221], v[48:49], v[234:235] op_sel_hi:[1,0] neg_lo:[0,1] neg_hi:[0,1]
	v_pk_fma_f32 v[180:181], v[220:221], v[220:221], v[180:181]
	v_pk_add_f32 v[218:219], v[56:57], v[236:237] op_sel_hi:[1,0] neg_lo:[0,1] neg_hi:[0,1]
	v_pk_fma_f32 v[182:183], v[218:219], v[218:219], v[182:183]
	v_pk_add_f32 v[220:221], v[64:65], v[150:151] op_sel_hi:[1,0] neg_lo:[0,1] neg_hi:[0,1]
	v_pk_fma_f32 v[184:185], v[220:221], v[220:221], v[184:185]
	v_pk_add_f32 v[218:219], v[66:67], v[132:133] op_sel_hi:[1,0] neg_lo:[0,1] neg_hi:[0,1]
	v_pk_fma_f32 v[170:171], v[218:219], v[218:219], v[170:171]
	v_pk_add_f32 v[220:221], v[74:75], v[134:135] op_sel_hi:[1,0] neg_lo:[0,1] neg_hi:[0,1]
	v_pk_fma_f32 v[172:173], v[220:221], v[220:221], v[172:173]
	v_pk_add_f32 v[218:219], v[82:83], v[136:137] op_sel_hi:[1,0] neg_lo:[0,1] neg_hi:[0,1]
	v_pk_fma_f32 v[174:175], v[218:219], v[218:219], v[174:175]
	v_pk_add_f32 v[220:221], v[90:91], v[138:139] op_sel_hi:[1,0] neg_lo:[0,1] neg_hi:[0,1]
	v_pk_fma_f32 v[176:177], v[220:221], v[220:221], v[176:177]
	v_pk_add_f32 v[218:219], v[2:3], v[232:233] op_sel_hi:[1,0] neg_lo:[0,1] neg_hi:[0,1]
	v_pk_fma_f32 v[178:179], v[218:219], v[218:219], v[178:179]
	v_pk_add_f32 v[220:221], v[10:11], v[234:235] op_sel_hi:[1,0] neg_lo:[0,1] neg_hi:[0,1]
	v_pk_fma_f32 v[180:181], v[220:221], v[220:221], v[180:181]
	v_pk_add_f32 v[218:219], v[18:19], v[236:237] op_sel_hi:[1,0] neg_lo:[0,1] neg_hi:[0,1]
	v_pk_fma_f32 v[182:183], v[218:219], v[218:219], v[182:183]
	v_pk_add_f32 v[220:221], v[26:27], v[150:151] op_sel_hi:[1,0] neg_lo:[0,1] neg_hi:[0,1]
	v_pk_fma_f32 v[184:185], v[220:221], v[220:221], v[184:185]
	v_pk_add_f32 v[218:219], v[68:69], v[132:133] op_sel_hi:[1,0] neg_lo:[0,1] neg_hi:[0,1]
	v_pk_fma_f32 v[170:171], v[218:219], v[218:219], v[170:171]
	v_pk_add_f32 v[220:221], v[76:77], v[134:135] op_sel_hi:[1,0] neg_lo:[0,1] neg_hi:[0,1]
	v_pk_fma_f32 v[172:173], v[220:221], v[220:221], v[172:173]
	v_pk_add_f32 v[218:219], v[84:85], v[136:137] op_sel_hi:[1,0] neg_lo:[0,1] neg_hi:[0,1]
	v_pk_fma_f32 v[174:175], v[218:219], v[218:219], v[174:175]
	v_pk_add_f32 v[220:221], v[92:93], v[138:139] op_sel_hi:[1,0] neg_lo:[0,1] neg_hi:[0,1]
	v_pk_fma_f32 v[176:177], v[220:221], v[220:221], v[176:177]
	v_pk_add_f32 v[218:219], v[4:5], v[232:233] op_sel_hi:[1,0] neg_lo:[0,1] neg_hi:[0,1]
	v_pk_fma_f32 v[178:179], v[218:219], v[218:219], v[178:179]
	v_pk_add_f32 v[220:221], v[12:13], v[234:235] op_sel_hi:[1,0] neg_lo:[0,1] neg_hi:[0,1]
	v_pk_fma_f32 v[180:181], v[220:221], v[220:221], v[180:181]
	v_pk_add_f32 v[218:219], v[20:21], v[236:237] op_sel_hi:[1,0] neg_lo:[0,1] neg_hi:[0,1]
	v_pk_fma_f32 v[182:183], v[218:219], v[218:219], v[182:183]
	v_pk_add_f32 v[220:221], v[28:29], v[150:151] op_sel_hi:[1,0] neg_lo:[0,1] neg_hi:[0,1]
	v_pk_fma_f32 v[184:185], v[220:221], v[220:221], v[184:185]
	v_pk_add_f32 v[218:219], v[70:71], v[132:133] op_sel_hi:[1,0] neg_lo:[0,1] neg_hi:[0,1]
	v_pk_fma_f32 v[170:171], v[218:219], v[218:219], v[170:171]
	v_pk_add_f32 v[220:221], v[78:79], v[134:135] op_sel_hi:[1,0] neg_lo:[0,1] neg_hi:[0,1]
	v_pk_fma_f32 v[172:173], v[220:221], v[220:221], v[172:173]
	v_pk_add_f32 v[218:219], v[86:87], v[136:137] op_sel_hi:[1,0] neg_lo:[0,1] neg_hi:[0,1]
	v_pk_fma_f32 v[174:175], v[218:219], v[218:219], v[174:175]
	v_pk_add_f32 v[220:221], v[94:95], v[138:139] op_sel_hi:[1,0] neg_lo:[0,1] neg_hi:[0,1]
	v_pk_fma_f32 v[176:177], v[220:221], v[220:221], v[176:177]
	v_pk_add_f32 v[218:219], v[6:7], v[232:233] op_sel_hi:[1,0] neg_lo:[0,1] neg_hi:[0,1]
	v_pk_fma_f32 v[178:179], v[218:219], v[218:219], v[178:179]
	v_pk_add_f32 v[220:221], v[14:15], v[234:235] op_sel_hi:[1,0] neg_lo:[0,1] neg_hi:[0,1]
	v_pk_fma_f32 v[180:181], v[220:221], v[220:221], v[180:181]
	v_pk_add_f32 v[218:219], v[22:23], v[236:237] op_sel_hi:[1,0] neg_lo:[0,1] neg_hi:[0,1]
	v_pk_fma_f32 v[182:183], v[218:219], v[218:219], v[182:183]
	v_pk_add_f32 v[220:221], v[30:31], v[150:151] op_sel_hi:[1,0] neg_lo:[0,1] neg_hi:[0,1]
	v_pk_fma_f32 v[184:185], v[220:221], v[220:221], v[184:185]
	v_pk_add_f32 v[218:219], v[72:73], v[132:133] op_sel_hi:[1,0] neg_lo:[0,1] neg_hi:[0,1]
	v_pk_fma_f32 v[170:171], v[218:219], v[218:219], v[170:171]
	v_pk_add_f32 v[220:221], v[80:81], v[134:135] op_sel_hi:[1,0] neg_lo:[0,1] neg_hi:[0,1]
	v_pk_fma_f32 v[172:173], v[220:221], v[220:221], v[172:173]
	v_pk_add_f32 v[218:219], v[88:89], v[136:137] op_sel_hi:[1,0] neg_lo:[0,1] neg_hi:[0,1]
	v_pk_fma_f32 v[174:175], v[218:219], v[218:219], v[174:175]
	v_pk_add_f32 v[220:221], v[96:97], v[138:139] op_sel_hi:[1,0] neg_lo:[0,1] neg_hi:[0,1]
	v_pk_fma_f32 v[176:177], v[220:221], v[220:221], v[176:177]
	v_pk_add_f32 v[218:219], v[8:9], v[232:233] op_sel_hi:[1,0] neg_lo:[0,1] neg_hi:[0,1]
	v_pk_fma_f32 v[178:179], v[218:219], v[218:219], v[178:179]
	v_pk_add_f32 v[220:221], v[16:17], v[234:235] op_sel_hi:[1,0] neg_lo:[0,1] neg_hi:[0,1]
	v_pk_fma_f32 v[180:181], v[220:221], v[220:221], v[180:181]
	v_pk_add_f32 v[218:219], v[24:25], v[236:237] op_sel_hi:[1,0] neg_lo:[0,1] neg_hi:[0,1]
	v_pk_fma_f32 v[182:183], v[218:219], v[218:219], v[182:183]
	v_pk_add_f32 v[220:221], v[32:33], v[150:151] op_sel_hi:[1,0] neg_lo:[0,1] neg_hi:[0,1]
	v_pk_fma_f32 v[184:185], v[220:221], v[220:221], v[184:185]
	v_add_f32_e32 v133, v170, v171
	v_add_f32_e32 v135, v172, v173
	v_add_f32_e32 v137, v174, v175
	v_add_f32_e32 v139, v176, v177
	v_add_f32_e32 v233, v178, v179
	v_add_f32_e32 v235, v180, v181
	v_add_f32_e32 v237, v182, v183
	v_add_f32_e32 v151, v184, v185
	v_add_f32_dpp v133, v133, v133 quad_perm:[1,0,3,2] row_mask:0xf bank_mask:0xf
	v_add_f32_dpp v135, v135, v135 quad_perm:[1,0,3,2] row_mask:0xf bank_mask:0xf
	v_add_f32_dpp v137, v137, v137 quad_perm:[1,0,3,2] row_mask:0xf bank_mask:0xf
	v_add_f32_dpp v139, v139, v139 quad_perm:[1,0,3,2] row_mask:0xf bank_mask:0xf
	v_add_f32_dpp v233, v233, v233 quad_perm:[1,0,3,2] row_mask:0xf bank_mask:0xf
	v_add_f32_dpp v235, v235, v235 quad_perm:[1,0,3,2] row_mask:0xf bank_mask:0xf
	v_add_f32_dpp v237, v237, v237 quad_perm:[1,0,3,2] row_mask:0xf bank_mask:0xf
	v_add_f32_dpp v151, v151, v151 quad_perm:[1,0,3,2] row_mask:0xf bank_mask:0xf
	v_add_f32_dpp v133, v133, v133 quad_perm:[2,3,0,1] row_mask:0xf bank_mask:0xf
	v_add_f32_dpp v135, v135, v135 quad_perm:[2,3,0,1] row_mask:0xf bank_mask:0xf
	v_add_f32_dpp v137, v137, v137 quad_perm:[2,3,0,1] row_mask:0xf bank_mask:0xf
	v_add_f32_dpp v139, v139, v139 quad_perm:[2,3,0,1] row_mask:0xf bank_mask:0xf
	v_add_f32_dpp v233, v233, v233 quad_perm:[2,3,0,1] row_mask:0xf bank_mask:0xf
	v_add_f32_dpp v235, v235, v235 quad_perm:[2,3,0,1] row_mask:0xf bank_mask:0xf
	v_add_f32_dpp v237, v237, v237 quad_perm:[2,3,0,1] row_mask:0xf bank_mask:0xf
	v_add_f32_dpp v151, v151, v151 quad_perm:[2,3,0,1] row_mask:0xf bank_mask:0xf
	v_add_f32_dpp v133, v133, v133 row_half_mirror row_mask:0xf bank_mask:0xf
	v_add_f32_dpp v135, v135, v135 row_half_mirror row_mask:0xf bank_mask:0xf
	v_add_f32_dpp v137, v137, v137 row_half_mirror row_mask:0xf bank_mask:0xf
	v_add_f32_dpp v139, v139, v139 row_half_mirror row_mask:0xf bank_mask:0xf
	v_add_f32_dpp v233, v233, v233 row_half_mirror row_mask:0xf bank_mask:0xf
	v_add_f32_dpp v235, v235, v235 row_half_mirror row_mask:0xf bank_mask:0xf
	v_add_f32_dpp v237, v237, v237 row_half_mirror row_mask:0xf bank_mask:0xf
	v_add_f32_dpp v151, v151, v151 row_half_mirror row_mask:0xf bank_mask:0xf
	v_add_f32_dpp v133, v133, v133 row_mirror row_mask:0xf bank_mask:0xf
	v_add_f32_dpp v135, v135, v135 row_mirror row_mask:0xf bank_mask:0xf
	v_add_f32_dpp v137, v137, v137 row_mirror row_mask:0xf bank_mask:0xf
	v_add_f32_dpp v139, v139, v139 row_mirror row_mask:0xf bank_mask:0xf
	v_add_f32_dpp v233, v233, v233 row_mirror row_mask:0xf bank_mask:0xf
	v_add_f32_dpp v235, v235, v235 row_mirror row_mask:0xf bank_mask:0xf
	v_add_f32_dpp v237, v237, v237 row_mirror row_mask:0xf bank_mask:0xf
	v_add_f32_dpp v151, v151, v151 row_mirror row_mask:0xf bank_mask:0xf
	s_lshr_b32 s0, s73, 8
	s_lshl_b32 s0, s0, 13
	s_add_u32 s40, s62, 0xf100000
	s_addc_u32 s41, s63, 0
	s_add_u32 s40, s40, s0
	s_addc_u32 s41, s41, 0
	s_lshr_b32 s0, s46, 8
	s_lshl_b32 s0, s0, 11
	v_add_u32_e32 v224, s0, v227
	s_mov_b32 exec_lo, 0x10001
	s_mov_b32 exec_hi, 0x10001
	global_store_dwordx2 v224, v[132:133], s[40:41] offset:0 sc1
	global_store_dwordx2 v224, v[134:135], s[40:41] offset:256 sc1
	global_store_dwordx2 v224, v[136:137], s[40:41] offset:512 sc1
	global_store_dwordx2 v224, v[138:139], s[40:41] offset:768 sc1
	global_store_dwordx2 v224, v[232:233], s[40:41] offset:1024 sc1
	global_store_dwordx2 v224, v[234:235], s[40:41] offset:1280 sc1
	global_store_dwordx2 v224, v[236:237], s[40:41] offset:1536 sc1
	global_store_dwordx2 v224, v[150:151], s[40:41] offset:1792 sc1
	s_mov_b64 exec, -1
	s_waitcnt vmcnt(0)
	s_barrier
	v_readfirstlane_b32 s98, v0
	s_nop 3
	s_lshr_b32 s98, s98, 6
	s_cmp_lg_u32 s98, 0
	s_cbranch_scc0 .Lp9_signal
	s_mov_b32 s38, 0x0
	s_mov_b32 s39, 0
	v_lshl_add_u64 v[154:155], v[230:231], 0, s[38:39]
	global_store_dwordx4 v[154:155], v[98:101], off
	global_store_dwordx4 v[154:155], v[102:105], off offset:16
	s_mov_b32 s38, 0x20000
	s_mov_b32 s39, 0
	v_lshl_add_u64 v[156:157], v[230:231], 0, s[38:39]
	global_store_dwordx4 v[156:157], v[106:109], off
	global_store_dwordx4 v[156:157], v[110:113], off offset:16
	s_mov_b32 s38, 0x40000
	s_mov_b32 s39, 0
	v_lshl_add_u64 v[154:155], v[230:231], 0, s[38:39]
	global_store_dwordx4 v[154:155], v[114:117], off
	global_store_dwordx4 v[154:155], v[118:121], off offset:16
	s_mov_b32 s38, 0x60000
	s_mov_b32 s39, 0
	v_lshl_add_u64 v[156:157], v[230:231], 0, s[38:39]
	global_store_dwordx4 v[156:157], v[122:125], off
	global_store_dwordx4 v[156:157], v[126:129], off offset:16
	s_mov_b32 s38, 0x200
	s_mov_b32 s39, 0
	v_lshl_add_u64 v[154:155], v[230:231], 0, s[38:39]
	global_store_dwordx4 v[154:155], v[66:69], off
	global_store_dwordx4 v[154:155], v[70:73], off offset:16
	s_mov_b32 s38, 0x20200
	s_mov_b32 s39, 0
	v_lshl_add_u64 v[156:157], v[230:231], 0, s[38:39]
	global_store_dwordx4 v[156:157], v[74:77], off
	global_store_dwordx4 v[156:157], v[78:81], off offset:16
	s_mov_b32 s38, 0x40200
	s_mov_b32 s39, 0
	v_lshl_add_u64 v[154:155], v[230:231], 0, s[38:39]
	global_store_dwordx4 v[154:155], v[82:85], off
	global_store_dwordx4 v[154:155], v[86:89], off offset:16
	s_mov_b32 s38, 0x60200
	s_mov_b32 s39, 0
	v_lshl_add_u64 v[156:157], v[230:231], 0, s[38:39]
	global_store_dwordx4 v[156:157], v[90:93], off
	global_store_dwordx4 v[156:157], v[94:97], off offset:16
	s_mov_b32 s38, 0x80000
	s_mov_b32 s39, 0
	v_lshl_add_u64 v[154:155], v[230:231], 0, s[38:39]
	global_store_dwordx4 v[154:155], v[34:37], off
	global_store_dwordx4 v[154:155], v[38:41], off offset:16
	s_mov_b32 s38, 0xa0000
	s_mov_b32 s39, 0
	v_lshl_add_u64 v[156:157], v[230:231], 0, s[38:39]
	global_store_dwordx4 v[156:157], v[42:45], off
	global_store_dwordx4 v[156:157], v[46:49], off offset:16
	s_mov_b32 s38, 0xc0000
	s_mov_b32 s39, 0
	v_lshl_add_u64 v[154:155], v[230:231], 0, s[38:39]
	global_store_dwordx4 v[154:155], v[50:53], off
	global_store_dwordx4 v[154:155], v[54:57], off offset:16
	s_mov_b32 s38, 0xe0000
	s_mov_b32 s39, 0
	v_lshl_add_u64 v[156:157], v[230:231], 0, s[38:39]
	global_store_dwordx4 v[156:157], v[58:61], off
	global_store_dwordx4 v[156:157], v[62:65], off offset:16
	s_mov_b32 s38, 0x80200
	s_mov_b32 s39, 0
	v_lshl_add_u64 v[154:155], v[230:231], 0, s[38:39]
	global_store_dwordx4 v[154:155], v[2:5], off
	global_store_dwordx4 v[154:155], v[6:9], off offset:16
	s_mov_b32 s38, 0xa0200
	s_mov_b32 s39, 0
	v_lshl_add_u64 v[156:157], v[230:231], 0, s[38:39]
	global_store_dwordx4 v[156:157], v[10:13], off
	global_store_dwordx4 v[156:157], v[14:17], off offset:16
	s_mov_b32 s38, 0xc0200
	s_mov_b32 s39, 0
	v_lshl_add_u64 v[154:155], v[230:231], 0, s[38:39]
	global_store_dwordx4 v[154:155], v[18:21], off
	global_store_dwordx4 v[154:155], v[22:25], off offset:16
	s_mov_b32 s38, 0xe0200
	s_mov_b32 s39, 0
	v_lshl_add_u64 v[156:157], v[230:231], 0, s[38:39]
	global_store_dwordx4 v[156:157], v[26:29], off
	global_store_dwordx4 v[156:157], v[30:33], off offset:16
	s_branch .Lp9_wait_done
.Lp9_signal:
	s_lshr_b32 s99, s73, 8
	s_lshl_b32 s99, s99, 2
	s_add_u32 s44, s62, 0xf71a100
	s_addc_u32 s45, s63, 0
	s_add_u32 s44, s44, s99
	s_addc_u32 s45, s45, 0
	v_mov_b32_e32 v238, 0
	v_mov_b32_e32 v239, 1
	s_mov_b64 exec, 1
	global_atomic_add v238, v239, s[44:45]
	s_mov_b32 s99, 0

.Lp9_wait_done:
	s_barrier
	v_and_b32_e32 v246, 7, v0
	v_lshrrev_b32_e32 v247, 2, v246
	v_and_b32_e32 v246, 3, v246
	v_lshlrev_b32_e32 v247, 10, v247
	v_lshl_add_u32 v246, v246, 8, v247
	v_add_u32_e32 v246, v246, v227
	v_add_u32_e32 v247, 0x1000, v246
	global_load_dwordx2 v[238:239], v246, s[40:41] sc1
	global_load_dwordx2 v[240:241], v246, s[40:41] offset:2048 sc1
	global_load_dwordx2 v[242:243], v247, s[40:41] sc1
	global_load_dwordx2 v[244:245], v247, s[40:41] offset:2048 sc1
	v_readfirstlane_b32 s98, v0
	s_nop 3
	s_lshr_b32 s98, s98, 6
	s_cmp_lg_u32 s98, 0
	s_cbranch_scc1 .Lp9_w0done
	s_mov_b32 s38, 0x0
	s_mov_b32 s39, 0
	v_lshl_add_u64 v[154:155], v[230:231], 0, s[38:39]
	global_store_dwordx4 v[154:155], v[98:101], off
	global_store_dwordx4 v[154:155], v[102:105], off offset:16
	s_mov_b32 s38, 0x20000
	s_mov_b32 s39, 0
	v_lshl_add_u64 v[156:157], v[230:231], 0, s[38:39]
	global_store_dwordx4 v[156:157], v[106:109], off
	global_store_dwordx4 v[156:157], v[110:113], off offset:16
	s_mov_b32 s38, 0x40000
	s_mov_b32 s39, 0
	v_lshl_add_u64 v[154:155], v[230:231], 0, s[38:39]
	global_store_dwordx4 v[154:155], v[114:117], off
	global_store_dwordx4 v[154:155], v[118:121], off offset:16
	s_mov_b32 s38, 0x60000
	s_mov_b32 s39, 0
	v_lshl_add_u64 v[156:157], v[230:231], 0, s[38:39]
	global_store_dwordx4 v[156:157], v[122:125], off
	global_store_dwordx4 v[156:157], v[126:129], off offset:16
	s_mov_b32 s38, 0x200
	s_mov_b32 s39, 0
	v_lshl_add_u64 v[154:155], v[230:231], 0, s[38:39]
	global_store_dwordx4 v[154:155], v[66:69], off
	global_store_dwordx4 v[154:155], v[70:73], off offset:16
	s_mov_b32 s38, 0x20200
	s_mov_b32 s39, 0
	v_lshl_add_u64 v[156:157], v[230:231], 0, s[38:39]
	global_store_dwordx4 v[156:157], v[74:77], off
	global_store_dwordx4 v[156:157], v[78:81], off offset:16
	s_mov_b32 s38, 0x40200
	s_mov_b32 s39, 0
	v_lshl_add_u64 v[154:155], v[230:231], 0, s[38:39]
	global_store_dwordx4 v[154:155], v[82:85], off
	global_store_dwordx4 v[154:155], v[86:89], off offset:16
	s_mov_b32 s38, 0x60200
	s_mov_b32 s39, 0
	v_lshl_add_u64 v[156:157], v[230:231], 0, s[38:39]
	global_store_dwordx4 v[156:157], v[90:93], off
	global_store_dwordx4 v[156:157], v[94:97], off offset:16
	s_mov_b32 s38, 0x80000
	s_mov_b32 s39, 0
	v_lshl_add_u64 v[154:155], v[230:231], 0, s[38:39]
	global_store_dwordx4 v[154:155], v[34:37], off
	global_store_dwordx4 v[154:155], v[38:41], off offset:16
	s_mov_b32 s38, 0xa0000
	s_mov_b32 s39, 0
	v_lshl_add_u64 v[156:157], v[230:231], 0, s[38:39]
	global_store_dwordx4 v[156:157], v[42:45], off
	global_store_dwordx4 v[156:157], v[46:49], off offset:16
	s_mov_b32 s38, 0xc0000
	s_mov_b32 s39, 0
	v_lshl_add_u64 v[154:155], v[230:231], 0, s[38:39]
	global_store_dwordx4 v[154:155], v[50:53], off
	global_store_dwordx4 v[154:155], v[54:57], off offset:16
	s_mov_b32 s38, 0xe0000
	s_mov_b32 s39, 0
	v_lshl_add_u64 v[156:157], v[230:231], 0, s[38:39]
	global_store_dwordx4 v[156:157], v[58:61], off
	global_store_dwordx4 v[156:157], v[62:65], off offset:16
	s_mov_b32 s38, 0x80200
	s_mov_b32 s39, 0
	v_lshl_add_u64 v[154:155], v[230:231], 0, s[38:39]
	global_store_dwordx4 v[154:155], v[2:5], off
	global_store_dwordx4 v[154:155], v[6:9], off offset:16
	s_mov_b32 s38, 0xa0200
	s_mov_b32 s39, 0
	v_lshl_add_u64 v[156:157], v[230:231], 0, s[38:39]
	global_store_dwordx4 v[156:157], v[10:13], off
	global_store_dwordx4 v[156:157], v[14:17], off offset:16
	s_mov_b32 s38, 0xc0200
	s_mov_b32 s39, 0
	v_lshl_add_u64 v[154:155], v[230:231], 0, s[38:39]
	global_store_dwordx4 v[154:155], v[18:21], off
	global_store_dwordx4 v[154:155], v[22:25], off offset:16
	s_mov_b32 s38, 0xe0200
	s_mov_b32 s39, 0
	v_lshl_add_u64 v[156:157], v[230:231], 0, s[38:39]
	global_store_dwordx4 v[156:157], v[26:29], off
	global_store_dwordx4 v[156:157], v[30:33], off offset:16
.Lp9_w0done:
	v_mov_b32_e32 v248, 0x3727c5ac
	v_and_b32_e32 v249, 48, v0
	v_lshlrev_b32_e32 v249, 2, v249
	s_waitcnt vmcnt(0)
	v_add_f32_e32 v250, v238, v240
	v_add_f32_e32 v246, v242, v244
	v_add_f32_e32 v250, v250, v246
	v_mul_f32_e32 v250, 0x3e800000, v250
	v_sub_f32_e32 v238, v238, v250
	v_sub_f32_e32 v240, v240, v250
	v_sub_f32_e32 v242, v242, v250
	v_sub_f32_e32 v244, v244, v250
	v_mul_f32_e32 v246, v238, v238
	v_fmac_f32_e32 v246, v240, v240
	v_fmac_f32_e32 v246, v242, v242
	v_fmac_f32_e32 v246, v244, v244
	v_add_f32_e32 v239, v239, v241
	v_add_f32_e32 v243, v243, v245
	v_add_f32_e32 v239, v239, v243
	v_fmamk_f32 v246, v246, 0x43800000, v239
	v_fmamk_f32 v246, v246, 0x3a800000, v248
	v_rsq_f32_e32 v251, v246
	s_nop 0
	v_add_u32_e32 v240, 0, v249
	ds_bpermute_b32 v132, v240, v250
	ds_bpermute_b32 v133, v240, v251
	v_add_u32_e32 v241, 4, v249
	ds_bpermute_b32 v134, v241, v250
	ds_bpermute_b32 v135, v241, v251
	v_add_u32_e32 v240, 8, v249
	ds_bpermute_b32 v136, v240, v250
	ds_bpermute_b32 v137, v240, v251
	v_add_u32_e32 v241, 12, v249
	ds_bpermute_b32 v138, v241, v250
	ds_bpermute_b32 v139, v241, v251
	v_add_u32_e32 v240, 16, v249
	ds_bpermute_b32 v232, v240, v250
	ds_bpermute_b32 v233, v240, v251
	v_add_u32_e32 v241, 20, v249
	ds_bpermute_b32 v234, v241, v250
	ds_bpermute_b32 v235, v241, v251
	v_add_u32_e32 v240, 24, v249
	ds_bpermute_b32 v236, v240, v250
	ds_bpermute_b32 v237, v240, v251
	v_add_u32_e32 v241, 28, v249
	ds_bpermute_b32 v150, v241, v250
	ds_bpermute_b32 v151, v241, v251
	s_waitcnt lgkmcnt(0)
	s_lshr_b32 s0, s46, 8
	s_cmp_lg_u32 s0, 0
	s_cbranch_scc1 .Lp9_nostats
	s_mov_b32 exec_lo, 0x10001
	s_mov_b32 exec_hi, 0x10001
	global_store_dwordx2 v227, v[132:133], s[52:53] offset:0
	global_store_dwordx2 v227, v[134:135], s[52:53] offset:256
	global_store_dwordx2 v227, v[136:137], s[52:53] offset:512
	global_store_dwordx2 v227, v[138:139], s[52:53] offset:768
	global_store_dwordx2 v227, v[232:233], s[52:53] offset:1024
	global_store_dwordx2 v227, v[234:235], s[52:53] offset:1280
	global_store_dwordx2 v227, v[236:237], s[52:53] offset:1536
	global_store_dwordx2 v227, v[150:151], s[52:53] offset:1792
	s_mov_b64 exec, -1

.LBB0_1595:
	v_add_u32_e32 v2, s1, v168
	v_ashrrev_i32_e32 v3, 31, v2
	v_add_u32_e32 v4, 16, v2
	v_lshlrev_b64 v[2:3], 11, v[2:3]
	v_ashrrev_i32_e32 v5, 31, v4
	v_lshl_add_u64 v[2:3], v[156:157], 0, v[2:3]
	v_lshlrev_b64 v[6:7], 11, v[4:5]
	global_load_dwordx4 v[2:5], v[2:3], off
	v_lshl_add_u64 v[6:7], v[156:157], 0, v[6:7]
	global_load_dwordx4 v[114:117], v[6:7], off
	s_add_i32 s1, s1, 32
	s_cmpk_eq_i32 s1, 0x80
	s_waitcnt vmcnt(1)
	v_mfma_f32_32x32x16_bf16 v[176:191], v[2:5], v[130:133], 0
	v_mfma_f32_32x32x16_bf16 v[192:207], v[2:5], v[134:137], 0
	v_mfma_f32_32x32x16_bf16 v[208:223], v[2:5], v[138:141], 0
	v_mfma_f32_32x32x16_bf16 v[224:239], v[2:5], v[142:145], 0
	s_waitcnt vmcnt(0)
	v_mfma_f32_32x32x16_bf16 v[50:65], v[114:117], v[130:133], 0
	v_mfma_f32_32x32x16_bf16 v[66:81], v[114:117], v[134:137], 0
	v_mfma_f32_32x32x16_bf16 v[82:97], v[114:117], v[138:141], 0
	v_mfma_f32_32x32x16_bf16 v[98:113], v[114:117], v[142:145], 0
	s_nop 7
	v_fma_f32 v244, -v153, v35, v176
	v_fma_f32 v245, v153, v34, v192
	v_fma_f32 v246, -v155, v119, v208
	v_fma_f32 v247, v155, v118, v224
	v_fma_f32 v240, v152, v34, v244
	v_fma_f32 v241, v152, v35, v245
	v_fma_f32 v242, v154, v118, v246
	v_fma_f32 v243, v154, v119, v247
	v_fma_f32 v244, -v153, v241, v177
	v_fma_f32 v245, v153, v240, v193
	v_fma_f32 v246, -v155, v243, v209
	v_fma_f32 v247, v155, v242, v225
	v_fma_f32 v34, v152, v240, v244
	v_fma_f32 v35, v152, v241, v245
	v_fma_f32 v118, v154, v242, v246
	v_fma_f32 v119, v154, v243, v247
	v_fma_f32 v244, -v153, v35, v178
	v_fma_f32 v245, v153, v34, v194
	v_fma_f32 v246, -v155, v119, v210
	v_fma_f32 v247, v155, v118, v226
	v_fma_f32 v240, v152, v34, v244
	v_fma_f32 v241, v152, v35, v245
	v_fma_f32 v242, v154, v118, v246
	v_fma_f32 v243, v154, v119, v247
	v_fma_f32 v244, -v153, v241, v179
	v_fma_f32 v245, v153, v240, v195
	v_fma_f32 v246, -v155, v243, v211
	v_fma_f32 v247, v155, v242, v227
	v_fma_f32 v34, v152, v240, v244
	v_fma_f32 v35, v152, v241, v245
	v_fma_f32 v118, v154, v242, v246
	v_fma_f32 v119, v154, v243, v247
	v_fma_f32 v244, -v153, v35, v180
	v_fma_f32 v245, v153, v34, v196
	v_fma_f32 v246, -v155, v119, v212
	v_fma_f32 v247, v155, v118, v228
	v_fma_f32 v240, v152, v34, v244
	v_fma_f32 v241, v152, v35, v245
	v_fma_f32 v242, v154, v118, v246
	v_fma_f32 v243, v154, v119, v247
	v_fma_f32 v244, -v153, v241, v181
	v_fma_f32 v245, v153, v240, v197
	v_fma_f32 v246, -v155, v243, v213
	v_fma_f32 v247, v155, v242, v229
	v_fma_f32 v34, v152, v240, v244
	v_fma_f32 v35, v152, v241, v245
	v_fma_f32 v118, v154, v242, v246
	v_fma_f32 v119, v154, v243, v247
	v_fma_f32 v244, -v153, v35, v182
	v_fma_f32 v245, v153, v34, v198
	v_fma_f32 v246, -v155, v119, v214
	v_fma_f32 v247, v155, v118, v230
	v_fma_f32 v240, v152, v34, v244
	v_fma_f32 v241, v152, v35, v245
	v_fma_f32 v242, v154, v118, v246
	v_fma_f32 v243, v154, v119, v247
	v_fma_f32 v244, -v153, v241, v183
	v_fma_f32 v245, v153, v240, v199
	v_fma_f32 v246, -v155, v243, v215
	v_fma_f32 v247, v155, v242, v231
	v_fma_f32 v34, v152, v240, v244
	v_fma_f32 v35, v152, v241, v245
	v_fma_f32 v118, v154, v242, v246
	v_fma_f32 v119, v154, v243, v247
	v_fma_f32 v244, -v153, v35, v184
	v_fma_f32 v245, v153, v34, v200
	v_fma_f32 v246, -v155, v119, v216
	v_fma_f32 v247, v155, v118, v232
	v_fma_f32 v240, v152, v34, v244
	v_fma_f32 v241, v152, v35, v245
	v_fma_f32 v242, v154, v118, v246
	v_fma_f32 v243, v154, v119, v247
	v_fma_f32 v244, -v153, v241, v185
	v_fma_f32 v245, v153, v240, v201
	v_fma_f32 v246, -v155, v243, v217
	v_fma_f32 v247, v155, v242, v233
	v_fma_f32 v34, v152, v240, v244
	v_fma_f32 v35, v152, v241, v245
	v_fma_f32 v118, v154, v242, v246
	v_fma_f32 v119, v154, v243, v247
	v_fma_f32 v244, -v153, v35, v186
	v_fma_f32 v245, v153, v34, v202
	v_fma_f32 v246, -v155, v119, v218
	v_fma_f32 v247, v155, v118, v234
	v_fma_f32 v240, v152, v34, v244
	v_fma_f32 v241, v152, v35, v245
	v_fma_f32 v242, v154, v118, v246
	v_fma_f32 v243, v154, v119, v247
	v_fma_f32 v244, -v153, v241, v187
	v_fma_f32 v245, v153, v240, v203
	v_fma_f32 v246, -v155, v243, v219
	v_fma_f32 v247, v155, v242, v235
	v_fma_f32 v34, v152, v240, v244
	v_fma_f32 v35, v152, v241, v245
	v_fma_f32 v118, v154, v242, v246
	v_fma_f32 v119, v154, v243, v247
	v_fma_f32 v244, -v153, v35, v188
	v_fma_f32 v245, v153, v34, v204
	v_fma_f32 v246, -v155, v119, v220
	v_fma_f32 v247, v155, v118, v236
	v_fma_f32 v240, v152, v34, v244
	v_fma_f32 v241, v152, v35, v245
	v_fma_f32 v242, v154, v118, v246
	v_fma_f32 v243, v154, v119, v247
	v_fma_f32 v244, -v153, v241, v189
	v_fma_f32 v245, v153, v240, v205
	v_fma_f32 v246, -v155, v243, v221
	v_fma_f32 v247, v155, v242, v237
	v_fma_f32 v34, v152, v240, v244
	v_fma_f32 v35, v152, v241, v245
	v_fma_f32 v118, v154, v242, v246
	v_fma_f32 v119, v154, v243, v247
	v_fma_f32 v244, -v153, v35, v190
	v_fma_f32 v245, v153, v34, v206
	v_fma_f32 v246, -v155, v119, v222
	v_fma_f32 v247, v155, v118, v238
	v_fma_f32 v240, v152, v34, v244
	v_fma_f32 v241, v152, v35, v245
	v_fma_f32 v242, v154, v118, v246
	v_fma_f32 v243, v154, v119, v247
	v_fma_f32 v244, -v153, v241, v191
	v_fma_f32 v245, v153, v240, v207
	v_fma_f32 v246, -v155, v243, v223
	v_fma_f32 v247, v155, v242, v239
	v_fma_f32 v34, v152, v240, v244
	v_fma_f32 v35, v152, v241, v245
	v_fma_f32 v118, v154, v242, v246
	v_fma_f32 v119, v154, v243, v247
	v_fma_f32 v244, -v153, v35, v50
	v_fma_f32 v245, v153, v34, v66
	v_fma_f32 v246, -v155, v119, v82
	v_fma_f32 v247, v155, v118, v98
	v_fma_f32 v240, v152, v34, v244
	v_fma_f32 v241, v152, v35, v245
	v_fma_f32 v242, v154, v118, v246
	v_fma_f32 v243, v154, v119, v247
	v_fma_f32 v244, -v153, v241, v51
	v_fma_f32 v245, v153, v240, v67
	v_fma_f32 v246, -v155, v243, v83
	v_fma_f32 v247, v155, v242, v99
	v_fma_f32 v34, v152, v240, v244
	v_fma_f32 v35, v152, v241, v245
	v_fma_f32 v118, v154, v242, v246
	v_fma_f32 v119, v154, v243, v247
	v_fma_f32 v244, -v153, v35, v52
	v_fma_f32 v245, v153, v34, v68
	v_fma_f32 v246, -v155, v119, v84
	v_fma_f32 v247, v155, v118, v100
	v_fma_f32 v240, v152, v34, v244
	v_fma_f32 v241, v152, v35, v245
	v_fma_f32 v242, v154, v118, v246
	v_fma_f32 v243, v154, v119, v247
	v_fma_f32 v244, -v153, v241, v53
	v_fma_f32 v245, v153, v240, v69
	v_fma_f32 v246, -v155, v243, v85
	v_fma_f32 v247, v155, v242, v101
	v_fma_f32 v34, v152, v240, v244
	v_fma_f32 v35, v152, v241, v245
	v_fma_f32 v118, v154, v242, v246
	v_fma_f32 v119, v154, v243, v247
	v_fma_f32 v244, -v153, v35, v54
	v_fma_f32 v245, v153, v34, v70
	v_fma_f32 v246, -v155, v119, v86
	v_fma_f32 v247, v155, v118, v102
	v_fma_f32 v240, v152, v34, v244
	v_fma_f32 v241, v152, v35, v245
	v_fma_f32 v242, v154, v118, v246
	v_fma_f32 v243, v154, v119, v247
	v_fma_f32 v244, -v153, v241, v55
	v_fma_f32 v245, v153, v240, v71
	v_fma_f32 v246, -v155, v243, v87
	v_fma_f32 v247, v155, v242, v103
	v_fma_f32 v34, v152, v240, v244
	v_fma_f32 v35, v152, v241, v245
	v_fma_f32 v118, v154, v242, v246
	v_fma_f32 v119, v154, v243, v247
	v_fma_f32 v244, -v153, v35, v56
	v_fma_f32 v245, v153, v34, v72
	v_fma_f32 v246, -v155, v119, v88
	v_fma_f32 v247, v155, v118, v104
	v_fma_f32 v240, v152, v34, v244
	v_fma_f32 v241, v152, v35, v245
	v_fma_f32 v242, v154, v118, v246
	v_fma_f32 v243, v154, v119, v247
	v_fma_f32 v244, -v153, v241, v57
	v_fma_f32 v245, v153, v240, v73
	v_fma_f32 v246, -v155, v243, v89
	v_fma_f32 v247, v155, v242, v105
	v_fma_f32 v34, v152, v240, v244
	v_fma_f32 v35, v152, v241, v245
	v_fma_f32 v118, v154, v242, v246
	v_fma_f32 v119, v154, v243, v247
	v_fma_f32 v244, -v153, v35, v58
	v_fma_f32 v245, v153, v34, v74
	v_fma_f32 v246, -v155, v119, v90
	v_fma_f32 v247, v155, v118, v106
	v_fma_f32 v240, v152, v34, v244
	v_fma_f32 v241, v152, v35, v245
	v_fma_f32 v242, v154, v118, v246
	v_fma_f32 v243, v154, v119, v247
	v_fma_f32 v244, -v153, v241, v59
	v_fma_f32 v245, v153, v240, v75
	v_fma_f32 v246, -v155, v243, v91
	v_fma_f32 v247, v155, v242, v107
	v_fma_f32 v34, v152, v240, v244
	v_fma_f32 v35, v152, v241, v245
	v_fma_f32 v118, v154, v242, v246
	v_fma_f32 v119, v154, v243, v247
	v_fma_f32 v244, -v153, v35, v60
	v_fma_f32 v245, v153, v34, v76
	v_fma_f32 v246, -v155, v119, v92
	v_fma_f32 v247, v155, v118, v108
	v_fma_f32 v240, v152, v34, v244
	v_fma_f32 v241, v152, v35, v245
	v_fma_f32 v242, v154, v118, v246
	v_fma_f32 v243, v154, v119, v247
	v_fma_f32 v244, -v153, v241, v61
	v_fma_f32 v245, v153, v240, v77
	v_fma_f32 v246, -v155, v243, v93
	v_fma_f32 v247, v155, v242, v109
	v_fma_f32 v34, v152, v240, v244
	v_fma_f32 v35, v152, v241, v245
	v_fma_f32 v118, v154, v242, v246
	v_fma_f32 v119, v154, v243, v247
	v_fma_f32 v244, -v153, v35, v62
	v_fma_f32 v245, v153, v34, v78
	v_fma_f32 v246, -v155, v119, v94
	v_fma_f32 v247, v155, v118, v110
	v_fma_f32 v240, v152, v34, v244
	v_fma_f32 v241, v152, v35, v245
	v_fma_f32 v242, v154, v118, v246
	v_fma_f32 v243, v154, v119, v247
	v_fma_f32 v244, -v153, v241, v63
	v_fma_f32 v245, v153, v240, v79
	v_fma_f32 v246, -v155, v243, v95
	v_fma_f32 v247, v155, v242, v111
	v_fma_f32 v34, v152, v240, v244
	v_fma_f32 v35, v152, v241, v245
	v_fma_f32 v118, v154, v242, v246
	v_fma_f32 v119, v154, v243, v247
	v_fma_f32 v244, -v153, v35, v64
	v_fma_f32 v245, v153, v34, v80
	v_fma_f32 v246, -v155, v119, v96
	v_fma_f32 v247, v155, v118, v112
	v_fma_f32 v240, v152, v34, v244
	v_fma_f32 v241, v152, v35, v245
	v_fma_f32 v242, v154, v118, v246
	v_fma_f32 v243, v154, v119, v247
	v_fma_f32 v244, -v153, v241, v65
	v_fma_f32 v245, v153, v240, v81
	v_fma_f32 v246, -v155, v243, v97
	v_fma_f32 v247, v155, v242, v113
	v_fma_f32 v34, v152, v240, v244
	v_fma_f32 v35, v152, v241, v245
	v_fma_f32 v118, v154, v242, v246
	v_fma_f32 v119, v154, v243, v247
	s_cbranch_scc0 .LBB0_1595
	s_nop 0
	v_lshlrev_b32_e32 v2, 7, v167
	v_or3_b32 v2, v2, v163, v166
	v_ashrrev_i32_e32 v3, 31, v2
	v_lshlrev_b64 v[2:3], 9, v[2:3]
	s_add_i32 s0, s0, s96
	v_lshl_add_u64 v[2:3], v[150:151], 0, v[2:3]
	s_cmpk_gt_i32 s0, 0x1ff
	global_store_dwordx2 v[2:3], v[34:35], off
	global_store_dwordx2 v[2:3], v[118:119], off offset:256
	s_cbranch_scc0 .LBB0_1594
